# plus: GEMM tile prologues no longer wait for the previous tile's epilogue stores; 5b3 loop-top counted wait
# speedup vs baseline: 1.0032x; 1.0010x over previous
; DI void glds2_stage(const u16* __restrict__ Wb, int K, const u16* __restrict__ Tb, int ldt, int k0, u16* lds, int w, int lane) {
;   const int rsub = lane >> 2;
; #pragma unroll
;   for (int i = 0; i < 4; ++i) {
;     const int grp = w + 4 * i;
;     const int row = grp * 16 + rsub;
;     const int c = (lane & 3) ^ ((row >> 2) & 3);
;     const unsigned off = (unsigned)(row * K + c * 8);
;     __builtin_amdgcn_global_load_lds((const unsigned*)(Wb + k0 + (size_t)off), (unsigned*)(lds + grp * 512), 16, 0, 0);
;   }
; #pragma unroll
;   for (int i = 0; i < 2; ++i) {
;     const int grp = w + 4 * i;
;     const int row = grp * 16 + rsub;
;     const int c = (lane & 3) ^ ((row >> 2) & 3);
;     const unsigned off = (unsigned)(row * ldt + c * 8);
;     __builtin_amdgcn_global_load_lds((const unsigned*)(Tb + k0 + (size_t)off), (unsigned*)(lds + 8192 + grp * 512), 16, 0, 0);
;   }
; }
; template <bool CT, bool MID, bool SSQ = false>
; DI void gemm2(f32x16 (&accA)[4], f32x16 (&accB)[4], const u16* __restrict__ Wb, const u16* __restrict__ Tb, int ldt, int K,
;               u16* smem, const float* s_mid, float* ssq_out = nullptr) {
;   float ssq_acc = 0.f;
;   const int tid = threadIdx.x, lane = tid & 63, w = __builtin_amdgcn_readfirstlane(tid >> 6), r = lane & 31, h = lane >> 5;
; #pragma unroll
;   for (int m = 0; m < 4; ++m) { accA[m] = zero16(); accB[m] = zero16(); }
;   const int nk = K / 32;
;   asm volatile("s_waitcnt vmcnt(0)" ::: "memory");
;   glds2_stage(Wb, K, Tb, ldt, 0, smem, w, lane);
;   glds2_stage(Wb, K, Tb, ldt, 32, smem + G2_STAGE, w, lane);
;   const int swr = (r >> 2) & 3;
.LBB0_173:
	s_andn2_b64 vcc, exec, s[6:7]
	s_mov_b64 s[6:7], -1
	s_cbranch_vccnz .LBB0_169
	s_ashr_i32 s11, s10, 31
	s_lshl_b32 s18, s39, 7
	s_lshl_b64 s[6:7], s[10:11], 19
	s_add_u32 s6, s14, s6
	s_addc_u32 s7, s15, s7
	s_ashr_i32 s19, s18, 31
	s_lshl_b64 s[20:21], s[18:19], 11
	s_add_u32 s20, s28, s20
	v_readfirstlane_b32 s11, v188
	s_addc_u32 s21, s29, s21
	s_lshr_b32 s11, s11, 6
	v_lshl_or_b32 v128, s11, 14, v209
	s_add_i32 s23, s11, 4
	v_lshlrev_b64 v[136:137], 1, v[128:129]
	s_lshl_b32 s19, s11, 10
	v_lshl_or_b32 v128, s23, 14, v209
	v_lshl_add_u64 v[0:1], s[6:7], 0, v[136:137]
	s_mov_b32 m0, s19
	v_lshlrev_b64 v[138:139], 1, v[128:129]
	s_lshl_b32 s24, s23, 9
	s_lshl_b32 s23, s23, 10
	s_add_i32 s25, s11, 8
	global_load_lds_dwordx4 v[0:1], off
	v_lshl_add_u64 v[2:3], s[6:7], 0, v[138:139]
	s_mov_b32 m0, s23
	v_lshl_or_b32 v128, s25, 14, v209
	s_lshl_b32 s26, s25, 9
	s_lshl_b32 s25, s25, 10
	s_add_i32 s27, s11, 12
	global_load_lds_dwordx4 v[2:3], off
	v_lshl_add_u64 v[4:5], v[128:129], 1, s[6:7]
	s_mov_b32 m0, s25
	v_lshl_or_b32 v140, s27, 14, v209
	v_mov_b32_e32 v141, v129
	s_lshl_b32 s40, s27, 9
	s_lshl_b32 s27, s27, 10
	global_load_lds_dwordx4 v[4:5], off
	v_lshl_add_u64 v[6:7], v[140:141], 1, s[6:7]
	s_mov_b32 m0, s27
	v_lshl_add_u64 v[8:9], s[20:21], 0, v[136:137]
	global_load_lds_dwordx4 v[6:7], off
	s_add_i32 m0, s19, 0x4000
	v_lshl_add_u64 v[10:11], s[20:21], 0, v[138:139]
	global_load_lds_dwordx4 v[8:9], off
	s_add_i32 m0, s23, 0x4000
	v_lshl_add_u64 v[0:1], v[0:1], 0, 64
	global_load_lds_dwordx4 v[10:11], off
	s_add_i32 m0, s19, 0x6000
	s_lshl_b32 s22, s11, 9
	global_load_lds_dwordx4 v[0:1], off
	v_lshl_add_u64 v[0:1], v[2:3], 0, 64
	s_add_i32 m0, s23, 0x6000
	v_mov_b32_e32 v142, 0
	global_load_lds_dwordx4 v[0:1], off
	v_lshl_add_u64 v[0:1], v[4:5], 0, 64
	s_add_i32 m0, s25, 0x6000
	s_lshl_b32 s11, s11, 11
	global_load_lds_dwordx4 v[0:1], off
	v_lshl_add_u64 v[0:1], v[6:7], 0, 64
	s_add_i32 m0, s27, 0x6000
	s_lshl_b32 s22, s22, 1
	global_load_lds_dwordx4 v[0:1], off
	v_lshl_add_u64 v[0:1], v[8:9], 0, 64
	s_add_i32 m0, s19, 0xa000
	s_mov_b32 s19, 0
	global_load_lds_dwordx4 v[0:1], off
	v_lshl_add_u64 v[0:1], v[10:11], 0, 64
	s_add_i32 m0, s23, 0xa000
	s_lshl_b32 s23, s24, 1
	global_load_lds_dwordx4 v[0:1], off
	s_lshl_b32 s24, s26, 1
	s_lshl_b32 s25, s40, 1
	s_mov_b32 s26, 0
	v_mov_b32_e32 v64, 0
	v_mov_b32_e32 v65, v142
	v_mov_b32_e32 v66, v142
	v_mov_b32_e32 v67, v142
	v_mov_b32_e32 v68, v142
	v_mov_b32_e32 v69, v142
	v_mov_b32_e32 v70, v142
	v_mov_b32_e32 v71, v142
	v_mov_b32_e32 v72, v142
	v_mov_b32_e32 v73, v142
	v_mov_b32_e32 v74, v142
	v_mov_b32_e32 v75, v142
	v_mov_b32_e32 v76, v142
	v_mov_b32_e32 v77, v142
	v_mov_b32_e32 v78, v142
	v_mov_b32_e32 v79, v142
	v_mov_b32_e32 v80, 0
	v_mov_b32_e32 v81, v142
	v_mov_b32_e32 v82, v142
	v_mov_b32_e32 v83, v142
	v_mov_b32_e32 v84, v142
	v_mov_b32_e32 v85, v142
	v_mov_b32_e32 v86, v142
	v_mov_b32_e32 v87, v142
	v_mov_b32_e32 v88, v142
	v_mov_b32_e32 v89, v142
	v_mov_b32_e32 v90, v142
	v_mov_b32_e32 v91, v142
	v_mov_b32_e32 v92, v142
	v_mov_b32_e32 v93, v142
	v_mov_b32_e32 v94, v142
	v_mov_b32_e32 v95, v142
	v_mov_b32_e32 v96, 0
	v_mov_b32_e32 v97, v142
	v_mov_b32_e32 v98, v142
	v_mov_b32_e32 v99, v142
	v_mov_b32_e32 v100, v142
	v_mov_b32_e32 v101, v142
	v_mov_b32_e32 v102, v142
	v_mov_b32_e32 v103, v142
	v_mov_b32_e32 v104, v142
	v_mov_b32_e32 v105, v142
	v_mov_b32_e32 v106, v142
	v_mov_b32_e32 v107, v142
	v_mov_b32_e32 v108, v142
	v_mov_b32_e32 v109, v142
	v_mov_b32_e32 v110, v142
	v_mov_b32_e32 v111, v142
	v_mov_b32_e32 v112, 0
	v_mov_b32_e32 v113, v142
	v_mov_b32_e32 v114, v142
	v_mov_b32_e32 v115, v142
	v_mov_b32_e32 v116, v142
	v_mov_b32_e32 v117, v142
	v_mov_b32_e32 v118, v142
	v_mov_b32_e32 v119, v142
	v_mov_b32_e32 v120, v142
	v_mov_b32_e32 v121, v142
	v_mov_b32_e32 v122, v142
	v_mov_b32_e32 v123, v142
	v_mov_b32_e32 v124, v142
	v_mov_b32_e32 v125, v142
	v_mov_b32_e32 v126, v142
	v_mov_b32_e32 v127, v142
	v_mov_b32_e32 v0, 0
	v_mov_b32_e32 v1, v142
	v_mov_b32_e32 v2, v142
	v_mov_b32_e32 v3, v142
	v_mov_b32_e32 v4, v142
	v_mov_b32_e32 v5, v142
	v_mov_b32_e32 v6, v142
	v_mov_b32_e32 v7, v142
	v_mov_b32_e32 v8, v142
	v_mov_b32_e32 v9, v142
	v_mov_b32_e32 v10, v142
	v_mov_b32_e32 v11, v142
	v_mov_b32_e32 v12, v142
	v_mov_b32_e32 v13, v142
	v_mov_b32_e32 v14, v142
	v_mov_b32_e32 v15, v142
	v_mov_b32_e32 v16, 0
	v_mov_b32_e32 v17, v142
	v_mov_b32_e32 v18, v142
	v_mov_b32_e32 v19, v142
	v_mov_b32_e32 v20, v142
	v_mov_b32_e32 v21, v142
	v_mov_b32_e32 v22, v142
	v_mov_b32_e32 v23, v142
	v_mov_b32_e32 v24, v142
	v_mov_b32_e32 v25, v142
	v_mov_b32_e32 v26, v142
	v_mov_b32_e32 v27, v142
	v_mov_b32_e32 v28, v142
	v_mov_b32_e32 v29, v142
	v_mov_b32_e32 v30, v142
	v_mov_b32_e32 v31, v142
	v_mov_b32_e32 v32, 0
	v_mov_b32_e32 v33, v142
	v_mov_b32_e32 v34, v142
	v_mov_b32_e32 v35, v142
	v_mov_b32_e32 v36, v142
	v_mov_b32_e32 v37, v142
	v_mov_b32_e32 v38, v142
	v_mov_b32_e32 v39, v142
	v_mov_b32_e32 v40, v142
	v_mov_b32_e32 v41, v142
	v_mov_b32_e32 v42, v142
	v_mov_b32_e32 v43, v142
	v_mov_b32_e32 v44, v142
	v_mov_b32_e32 v45, v142
	v_mov_b32_e32 v46, v142
	v_mov_b32_e32 v47, v142
	v_mov_b32_e32 v48, 0
	v_mov_b32_e32 v49, v142
	v_mov_b32_e32 v50, v142
	v_mov_b32_e32 v51, v142
	v_mov_b32_e32 v52, v142
	v_mov_b32_e32 v53, v142
	v_mov_b32_e32 v54, v142
	v_mov_b32_e32 v55, v142
	v_mov_b32_e32 v56, v142
	v_mov_b32_e32 v57, v142
	v_mov_b32_e32 v58, v142
	v_mov_b32_e32 v59, v142
	v_mov_b32_e32 v60, v142
	v_mov_b32_e32 v61, v142
	v_mov_b32_e32 v62, v142
	v_mov_b32_e32 v63, v142

; DI void glds2_stage(const u16* __restrict__ Wb, int K, const u16* __restrict__ Tb, int ldt, int k0, u16* lds, int w, int lane) {
;   const int rsub = lane >> 2;
; #pragma unroll
;   for (int i = 0; i < 4; ++i) {
;     const int grp = w + 4 * i;
;     const int row = grp * 16 + rsub;
;     const int c = (lane & 3) ^ ((row >> 2) & 3);
;     const unsigned off = (unsigned)(row * K + c * 8);
;     __builtin_amdgcn_global_load_lds((const unsigned*)(Wb + k0 + (size_t)off), (unsigned*)(lds + grp * 512), 16, 0, 0);
;   }
; #pragma unroll
;   for (int i = 0; i < 2; ++i) {
;     const int grp = w + 4 * i;
;     const int row = grp * 16 + rsub;
;     const int c = (lane & 3) ^ ((row >> 2) & 3);
;     const unsigned off = (unsigned)(row * ldt + c * 8);
;     __builtin_amdgcn_global_load_lds((const unsigned*)(Tb + k0 + (size_t)off), (unsigned*)(lds + 8192 + grp * 512), 16, 0, 0);
;   }
; }
; template <bool CT, bool MID, bool SSQ = false>
; DI void gemm2(f32x16 (&accA)[4], f32x16 (&accB)[4], const u16* __restrict__ Wb, const u16* __restrict__ Tb, int ldt, int K,
;               u16* smem, const float* s_mid, float* ssq_out = nullptr) {
;   float ssq_acc = 0.f;
;   const int tid = threadIdx.x, lane = tid & 63, w = __builtin_amdgcn_readfirstlane(tid >> 6), r = lane & 31, h = lane >> 5;
; #pragma unroll
;   for (int m = 0; m < 4; ++m) { accA[m] = zero16(); accB[m] = zero16(); }
;   const int nk = K / 32;
;   asm volatile("s_waitcnt vmcnt(0)" ::: "memory");
;   glds2_stage(Wb, K, Tb, ldt, 0, smem, w, lane);
;   glds2_stage(Wb, K, Tb, ldt, 32, smem + G2_STAGE, w, lane);
;   const int swr = (r >> 2) & 3;
.LBB0_211:
	s_add_i32 s10, s24, 0xffffee00
	s_ashr_i32 s11, s10, 31
	s_lshr_b32 s11, s11, 30
	s_add_i32 s11, s10, s11
	s_ashr_i32 s46, s11, 2
	s_and_b32 s11, s11, -4
	s_sub_i32 s18, s10, s11
	s_ashr_i32 s19, s18, 31
	s_lshl_b32 s10, s46, 7
	s_lshl_b64 s[20:21], s[18:19], 19
	s_add_u32 s20, s25, s20
	s_addc_u32 s21, s26, s21
	s_ashr_i32 s11, s10, 31
	s_lshl_b64 s[22:23], s[10:11], 11
	s_add_u32 s22, s27, s22
	v_readfirstlane_b32 s11, v188
	s_addc_u32 s23, s28, s23
	s_lshr_b32 s11, s11, 6
	v_lshl_or_b32 v128, s11, 14, v209
	s_add_i32 s48, s11, 4
	v_lshlrev_b64 v[134:135], 1, v[128:129]
	s_lshl_b32 s47, s11, 10
	v_lshl_or_b32 v128, s48, 14, v209
	v_lshl_add_u64 v[0:1], s[20:21], 0, v[134:135]
	s_mov_b32 m0, s47
	v_lshlrev_b64 v[136:137], 1, v[128:129]
	s_lshl_b32 s49, s48, 9
	s_lshl_b32 s48, s48, 10
	s_add_i32 s50, s11, 8
	global_load_lds_dwordx4 v[0:1], off
	v_lshl_add_u64 v[2:3], s[20:21], 0, v[136:137]
	s_mov_b32 m0, s48
	v_lshl_or_b32 v128, s50, 14, v209
	s_lshl_b32 s51, s50, 9
	s_lshl_b32 s50, s50, 10
	s_add_i32 s52, s11, 12
	global_load_lds_dwordx4 v[2:3], off
	v_lshl_add_u64 v[4:5], v[128:129], 1, s[20:21]
	s_mov_b32 m0, s50
	v_lshl_or_b32 v138, s52, 14, v209
	v_mov_b32_e32 v139, v129
	s_lshl_b32 s53, s52, 9
	s_lshl_b32 s52, s52, 10
	global_load_lds_dwordx4 v[4:5], off
	v_lshl_add_u64 v[6:7], v[138:139], 1, s[20:21]
	s_mov_b32 m0, s52
	v_lshl_add_u64 v[8:9], s[22:23], 0, v[134:135]
	global_load_lds_dwordx4 v[6:7], off
	s_add_i32 m0, s47, 0x4000
	v_lshl_add_u64 v[10:11], s[22:23], 0, v[136:137]
	global_load_lds_dwordx4 v[8:9], off
	s_add_i32 m0, s48, 0x4000
	v_lshl_add_u64 v[0:1], v[0:1], 0, 64
	global_load_lds_dwordx4 v[10:11], off
	s_add_i32 m0, s47, 0x6000
	s_lshl_b32 s19, s11, 9
	global_load_lds_dwordx4 v[0:1], off
	v_lshl_add_u64 v[0:1], v[2:3], 0, 64
	s_add_i32 m0, s48, 0x6000
	s_lshl_b32 s11, s11, 11
	global_load_lds_dwordx4 v[0:1], off
	v_lshl_add_u64 v[0:1], v[4:5], 0, 64
	s_add_i32 m0, s50, 0x6000
	s_lshl_b32 s19, s19, 1
	global_load_lds_dwordx4 v[0:1], off
	v_lshl_add_u64 v[0:1], v[6:7], 0, 64
	s_add_i32 m0, s52, 0x6000
	v_mov_b32_e32 v140, v129
	global_load_lds_dwordx4 v[0:1], off
	v_lshl_add_u64 v[0:1], v[8:9], 0, 64
	s_add_i32 m0, s47, 0xa000
	s_lshl_b32 s47, s49, 1
	global_load_lds_dwordx4 v[0:1], off
	v_lshl_add_u64 v[0:1], v[10:11], 0, 64
	s_add_i32 m0, s48, 0xa000
	s_lshl_b32 s48, s51, 1
	global_load_lds_dwordx4 v[0:1], off
	s_lshl_b32 s49, s53, 1
	s_mov_b32 s50, 0
	s_mov_b32 s51, 0
	v_mov_b32_e32 v64, v129
	v_mov_b32_e32 v65, v129
	v_mov_b32_e32 v66, v129
	v_mov_b32_e32 v67, v129
	v_mov_b32_e32 v68, v129
	v_mov_b32_e32 v69, v129
	v_mov_b32_e32 v70, v129
	v_mov_b32_e32 v71, v129
	v_mov_b32_e32 v72, v129
	v_mov_b32_e32 v73, v129
	v_mov_b32_e32 v74, v129
	v_mov_b32_e32 v75, v129
	v_mov_b32_e32 v76, v129
	v_mov_b32_e32 v77, v129
	v_mov_b32_e32 v78, v129
	v_mov_b32_e32 v79, v129
	v_mov_b32_e32 v80, v129
	v_mov_b32_e32 v81, v129
	v_mov_b32_e32 v82, v129
	v_mov_b32_e32 v83, v129
	v_mov_b32_e32 v84, v129
	v_mov_b32_e32 v85, v129
	v_mov_b32_e32 v86, v129
	v_mov_b32_e32 v87, v129
	v_mov_b32_e32 v88, v129
	v_mov_b32_e32 v89, v129
	v_mov_b32_e32 v90, v129
	v_mov_b32_e32 v91, v129
	v_mov_b32_e32 v92, v129
	v_mov_b32_e32 v93, v129
	v_mov_b32_e32 v94, v129
	v_mov_b32_e32 v95, v129
	v_mov_b32_e32 v96, v129
	v_mov_b32_e32 v97, v129
	v_mov_b32_e32 v98, v129
	v_mov_b32_e32 v99, v129
	v_mov_b32_e32 v100, v129
	v_mov_b32_e32 v101, v129
	v_mov_b32_e32 v102, v129
	v_mov_b32_e32 v103, v129
	v_mov_b32_e32 v104, v129
	v_mov_b32_e32 v105, v129
	v_mov_b32_e32 v106, v129
	v_mov_b32_e32 v107, v129
	v_mov_b32_e32 v108, v129
	v_mov_b32_e32 v109, v129
	v_mov_b32_e32 v110, v129
	v_mov_b32_e32 v111, v129
	v_mov_b32_e32 v112, v129
	v_mov_b32_e32 v113, v129
	v_mov_b32_e32 v114, v129
	v_mov_b32_e32 v115, v129
	v_mov_b32_e32 v116, v129
	v_mov_b32_e32 v117, v129
	v_mov_b32_e32 v118, v129
	v_mov_b32_e32 v119, v129
	v_mov_b32_e32 v120, v129
	v_mov_b32_e32 v121, v129
	v_mov_b32_e32 v122, v129
	v_mov_b32_e32 v123, v129
	v_mov_b32_e32 v124, v129
	v_mov_b32_e32 v125, v129
	v_mov_b32_e32 v126, v129
	v_mov_b32_e32 v127, v129
	v_mov_b32_e32 v0, v129
	v_mov_b32_e32 v1, v129
	v_mov_b32_e32 v2, v129
	v_mov_b32_e32 v3, v129
	v_mov_b32_e32 v4, v129
	v_mov_b32_e32 v5, v129
	v_mov_b32_e32 v6, v129
	v_mov_b32_e32 v7, v129
	v_mov_b32_e32 v8, v129
	v_mov_b32_e32 v9, v129
	v_mov_b32_e32 v10, v129
	v_mov_b32_e32 v11, v129
	v_mov_b32_e32 v12, v129
	v_mov_b32_e32 v13, v129
	v_mov_b32_e32 v14, v129
	v_mov_b32_e32 v15, v129
	v_mov_b32_e32 v16, v129
	v_mov_b32_e32 v17, v129
	v_mov_b32_e32 v18, v129
	v_mov_b32_e32 v19, v129
	v_mov_b32_e32 v20, v129
	v_mov_b32_e32 v21, v129
	v_mov_b32_e32 v22, v129
	v_mov_b32_e32 v23, v129
	v_mov_b32_e32 v24, v129
	v_mov_b32_e32 v25, v129
	v_mov_b32_e32 v26, v129
	v_mov_b32_e32 v27, v129
	v_mov_b32_e32 v28, v129
	v_mov_b32_e32 v29, v129
	v_mov_b32_e32 v30, v129
	v_mov_b32_e32 v31, v129
	v_mov_b32_e32 v32, v129
	v_mov_b32_e32 v33, v129
	v_mov_b32_e32 v34, v129
	v_mov_b32_e32 v35, v129
	v_mov_b32_e32 v36, v129
	v_mov_b32_e32 v37, v129
	v_mov_b32_e32 v38, v129
	v_mov_b32_e32 v39, v129
	v_mov_b32_e32 v40, v129
	v_mov_b32_e32 v41, v129
	v_mov_b32_e32 v42, v129
	v_mov_b32_e32 v43, v129
	v_mov_b32_e32 v44, v129
	v_mov_b32_e32 v45, v129
	v_mov_b32_e32 v46, v129
	v_mov_b32_e32 v47, v129
	v_mov_b32_e32 v48, v129
	v_mov_b32_e32 v49, v129
	v_mov_b32_e32 v50, v129
	v_mov_b32_e32 v51, v129
	v_mov_b32_e32 v52, v129
	v_mov_b32_e32 v53, v129
	v_mov_b32_e32 v54, v129
	v_mov_b32_e32 v55, v129
	v_mov_b32_e32 v56, v129
	v_mov_b32_e32 v57, v129
	v_mov_b32_e32 v58, v129
	v_mov_b32_e32 v59, v129
	v_mov_b32_e32 v60, v129
	v_mov_b32_e32 v61, v129
	v_mov_b32_e32 v62, v129
	v_mov_b32_e32 v63, v129

; DI void glds2_stage(const u16* __restrict__ Wb, int K, const u16* __restrict__ Tb, int ldt, int k0, u16* lds, int w, int lane) {
;   const int rsub = lane >> 2;
; #pragma unroll
;   for (int i = 0; i < 4; ++i) {
;     const int grp = w + 4 * i;
;     const int row = grp * 16 + rsub;
;     const int c = (lane & 3) ^ ((row >> 2) & 3);
;     const unsigned off = (unsigned)(row * K + c * 8);
;     __builtin_amdgcn_global_load_lds((const unsigned*)(Wb + k0 + (size_t)off), (unsigned*)(lds + grp * 512), 16, 0, 0);
;   }
; #pragma unroll
;   for (int i = 0; i < 2; ++i) {
;     const int grp = w + 4 * i;
;     const int row = grp * 16 + rsub;
;     const int c = (lane & 3) ^ ((row >> 2) & 3);
;     const unsigned off = (unsigned)(row * ldt + c * 8);
;     __builtin_amdgcn_global_load_lds((const unsigned*)(Tb + k0 + (size_t)off), (unsigned*)(lds + 8192 + grp * 512), 16, 0, 0);
;   }
; }
; template <bool CT, bool MID, bool SSQ = false>
; DI void gemm2(f32x16 (&accA)[4], f32x16 (&accB)[4], const u16* __restrict__ Wb, const u16* __restrict__ Tb, int ldt, int K,
;               u16* smem, const float* s_mid, float* ssq_out = nullptr) {
;   float ssq_acc = 0.f;
;   const int tid = threadIdx.x, lane = tid & 63, w = __builtin_amdgcn_readfirstlane(tid >> 6), r = lane & 31, h = lane >> 5;
; #pragma unroll
;   for (int m = 0; m < 4; ++m) { accA[m] = zero16(); accB[m] = zero16(); }
;   const int nk = K / 32;
;   asm volatile("s_waitcnt vmcnt(0)" ::: "memory");
;   glds2_stage(Wb, K, Tb, ldt, 0, smem, w, lane);
;   glds2_stage(Wb, K, Tb, ldt, 32, smem + G2_STAGE, w, lane);
;   const int swr = (r >> 2) & 3;
; template <int WHICH>
; DI void phase_resid_gemm(const Params& p, u16* smem) {
;     ...
;       __syncthreads();
;       gemm2<false, true>(accA, accB, WT + (size_t)nt2 * 256 * K, (const u16*)(ws + OFF_OAB) + (size_t)t0 * 1024, 1024, K, smem, s_rs2);
.LBB0_297:
	s_or_b64 exec, exec, s[28:29]
	s_and_b32 s70, s70, 3
	s_lshl_b32 s10, s70, 19
	s_add_u32 s10, s31, s10
	s_addc_u32 s11, s34, 0
	s_lshl_b32 s71, s71, 18
	s_add_u32 s28, s25, s71
	v_readfirstlane_b32 s72, v188
	s_addc_u32 s29, s30, 0
	s_lshr_b32 s73, s72, 6
	v_lshl_or_b32 v192, s73, 14, v209
	s_add_i32 s75, s73, 4
	v_lshlrev_b64 v[128:129], 1, v[192:193]
	s_lshl_b32 s74, s73, 10
	v_lshl_or_b32 v192, s75, 14, v209
	s_waitcnt lgkmcnt(0)
	s_barrier
	v_lshl_add_u64 v[0:1], s[10:11], 0, v[128:129]
	s_mov_b32 m0, s74
	v_lshlrev_b64 v[130:131], 1, v[192:193]
	s_lshl_b32 s76, s75, 10
	s_add_i32 s77, s73, 8
	global_load_lds_dwordx4 v[0:1], off
	v_lshl_add_u64 v[2:3], s[10:11], 0, v[130:131]
	s_mov_b32 m0, s76
	v_lshl_or_b32 v192, s77, 14, v209
	s_lshl_b32 s78, s77, 10
	s_add_i32 s79, s73, 12
	global_load_lds_dwordx4 v[2:3], off
	v_lshl_add_u64 v[4:5], v[192:193], 1, s[10:11]
	s_mov_b32 m0, s78
	v_lshl_or_b32 v132, s79, 14, v209
	v_mov_b32_e32 v133, v193
	s_lshl_b32 s80, s79, 10
	global_load_lds_dwordx4 v[4:5], off
	v_lshl_add_u64 v[6:7], v[132:133], 1, s[10:11]
	s_mov_b32 m0, s80
	v_lshl_add_u64 v[8:9], s[28:29], 0, v[128:129]
	global_load_lds_dwordx4 v[6:7], off
	s_add_i32 m0, s74, 0x4000
	v_lshl_add_u64 v[10:11], s[28:29], 0, v[130:131]
	global_load_lds_dwordx4 v[8:9], off
	s_add_i32 m0, s76, 0x4000
	v_lshl_add_u64 v[0:1], v[0:1], 0, 64
	global_load_lds_dwordx4 v[10:11], off
	s_add_i32 m0, s74, 0x6000
	s_lshl_b32 s72, s72, 5
	global_load_lds_dwordx4 v[0:1], off
	v_lshl_add_u64 v[0:1], v[2:3], 0, 64
	s_add_i32 m0, s76, 0x6000
	v_mov_b32_e32 v14, v193
	global_load_lds_dwordx4 v[0:1], off
	v_lshl_add_u64 v[0:1], v[4:5], 0, 64
	s_add_i32 m0, s78, 0x6000
	v_mov_b32_e32 v15, v193
	global_load_lds_dwordx4 v[0:1], off
	v_lshl_add_u64 v[0:1], v[6:7], 0, 64
	s_add_i32 m0, s80, 0x6000
	s_lshl_b32 s75, s75, 9
	global_load_lds_dwordx4 v[0:1], off
	v_lshl_add_u64 v[0:1], v[8:9], 0, 64
	s_add_i32 m0, s74, 0xa000
	s_lshl_b32 s74, s73, 9
	global_load_lds_dwordx4 v[0:1], off
	v_lshl_add_u64 v[0:1], v[10:11], 0, 64
	s_add_i32 m0, s76, 0xa000
	s_lshl_b32 s76, s77, 9
	global_load_lds_dwordx4 v[0:1], off
	s_lshl_b32 s77, s79, 9
	s_and_b32 s78, s72, 0xfffff800
	v_mov_b32_e32 v0, v193
	v_mov_b32_e32 v1, v193
	v_mov_b32_e32 v2, v193
	v_mov_b32_e32 v3, v193
	v_mov_b32_e32 v4, v193
	v_mov_b32_e32 v5, v193
	v_mov_b32_e32 v6, v193
	v_mov_b32_e32 v7, v193
	v_mov_b32_e32 v8, v193
	v_mov_b32_e32 v9, v193
	v_mov_b32_e32 v10, v193
	v_mov_b32_e32 v11, v193
	v_mov_b32_e32 v12, v193
	v_mov_b32_e32 v13, v193
	v_mov_b64_e32 v[30:31], v[14:15]
	v_mov_b64_e32 v[46:47], v[14:15]
	v_mov_b64_e32 v[62:63], v[14:15]
	v_mov_b64_e32 v[78:79], v[14:15]
	v_mov_b64_e32 v[94:95], v[14:15]
	v_mov_b64_e32 v[110:111], v[14:15]
	v_mov_b64_e32 v[126:127], v[14:15]
	s_mov_b32 s73, 0
	s_lshl_b32 s72, s74, 1
	s_lshl_b32 s74, s75, 1
	s_lshl_b32 s75, s76, 1
	s_lshl_b32 s76, s77, 1
	s_lshl_b32 s77, s78, 1
	v_mov_b64_e32 v[28:29], v[12:13]
	v_mov_b64_e32 v[26:27], v[10:11]
	v_mov_b64_e32 v[24:25], v[8:9]
	v_mov_b64_e32 v[22:23], v[6:7]
	v_mov_b64_e32 v[20:21], v[4:5]
	v_mov_b64_e32 v[18:19], v[2:3]
	v_mov_b64_e32 v[16:17], v[0:1]
	v_mov_b64_e32 v[44:45], v[12:13]
	v_mov_b64_e32 v[42:43], v[10:11]
	v_mov_b64_e32 v[40:41], v[8:9]
	v_mov_b64_e32 v[38:39], v[6:7]
	v_mov_b64_e32 v[36:37], v[4:5]
	v_mov_b64_e32 v[34:35], v[2:3]
	v_mov_b64_e32 v[32:33], v[0:1]
	v_mov_b64_e32 v[60:61], v[12:13]
	v_mov_b64_e32 v[58:59], v[10:11]
	v_mov_b64_e32 v[56:57], v[8:9]
	v_mov_b64_e32 v[54:55], v[6:7]
	v_mov_b64_e32 v[52:53], v[4:5]
	v_mov_b64_e32 v[50:51], v[2:3]
	v_mov_b64_e32 v[48:49], v[0:1]
	v_mov_b64_e32 v[76:77], v[12:13]
	v_mov_b64_e32 v[74:75], v[10:11]
	v_mov_b64_e32 v[72:73], v[8:9]
	v_mov_b64_e32 v[70:71], v[6:7]
	v_mov_b64_e32 v[68:69], v[4:5]
	v_mov_b64_e32 v[66:67], v[2:3]
	v_mov_b64_e32 v[64:65], v[0:1]
	v_mov_b64_e32 v[92:93], v[12:13]
	v_mov_b64_e32 v[90:91], v[10:11]
	v_mov_b64_e32 v[88:89], v[8:9]
	v_mov_b64_e32 v[86:87], v[6:7]
	v_mov_b64_e32 v[84:85], v[4:5]
	v_mov_b64_e32 v[82:83], v[2:3]
	v_mov_b64_e32 v[80:81], v[0:1]
	v_mov_b64_e32 v[108:109], v[12:13]
	v_mov_b64_e32 v[106:107], v[10:11]
	v_mov_b64_e32 v[104:105], v[8:9]
	v_mov_b64_e32 v[102:103], v[6:7]
	v_mov_b64_e32 v[100:101], v[4:5]
	v_mov_b64_e32 v[98:99], v[2:3]
	v_mov_b64_e32 v[96:97], v[0:1]
	v_mov_b64_e32 v[124:125], v[12:13]
	v_mov_b64_e32 v[122:123], v[10:11]
	v_mov_b64_e32 v[120:121], v[8:9]
	v_mov_b64_e32 v[118:119], v[6:7]
	v_mov_b64_e32 v[116:117], v[4:5]
	v_mov_b64_e32 v[114:115], v[2:3]
	v_mov_b64_e32 v[112:113], v[0:1]
	s_mov_b32 s78, 0
	s_branch .LBB0_299

; DI void glds2_stage(const u16* __restrict__ Wb, int K, const u16* __restrict__ Tb, int ldt, int k0, u16* lds, int w, int lane) {
;   const int rsub = lane >> 2;
; #pragma unroll
;   for (int i = 0; i < 4; ++i) {
;     const int grp = w + 4 * i;
;     const int row = grp * 16 + rsub;
;     const int c = (lane & 3) ^ ((row >> 2) & 3);
;     const unsigned off = (unsigned)(row * K + c * 8);
;     __builtin_amdgcn_global_load_lds((const unsigned*)(Wb + k0 + (size_t)off), (unsigned*)(lds + grp * 512), 16, 0, 0);
;   }
; #pragma unroll
;   for (int i = 0; i < 2; ++i) {
;     const int grp = w + 4 * i;
;     const int row = grp * 16 + rsub;
;     const int c = (lane & 3) ^ ((row >> 2) & 3);
;     const unsigned off = (unsigned)(row * ldt + c * 8);
;     __builtin_amdgcn_global_load_lds((const unsigned*)(Tb + k0 + (size_t)off), (unsigned*)(lds + 8192 + grp * 512), 16, 0, 0);
;   }
; }
; template <bool CT, bool MID, bool SSQ = false>
; DI void gemm2(f32x16 (&accA)[4], f32x16 (&accB)[4], const u16* __restrict__ Wb, const u16* __restrict__ Tb, int ldt, int K,
;               u16* smem, const float* s_mid, float* ssq_out = nullptr) {
;   float ssq_acc = 0.f;
;   const int tid = threadIdx.x, lane = tid & 63, w = __builtin_amdgcn_readfirstlane(tid >> 6), r = lane & 31, h = lane >> 5;
; #pragma unroll
;   for (int m = 0; m < 4; ++m) { accA[m] = zero16(); accB[m] = zero16(); }
;   const int nk = K / 32;
;   asm volatile("s_waitcnt vmcnt(0)" ::: "memory");
;   glds2_stage(Wb, K, Tb, ldt, 0, smem, w, lane);
;   glds2_stage(Wb, K, Tb, ldt, 32, smem + G2_STAGE, w, lane);
;   const int swr = (r >> 2) & 3;
.LBB0_310:
	s_lshl_b32 s9, s8, 2
	s_and_b32 s9, s9, 0x3f8
	s_and_b32 s20, s8, 1
	s_or_b32 s38, s9, s55
	s_lshl_b32 s8, s20, 19
	s_add_u32 s8, s31, s8
	s_addc_u32 s9, s34, 0
	s_lshl_b32 s28, s38, 18
	s_add_u32 s28, s25, s28
	v_readfirstlane_b32 s39, v188
	s_addc_u32 s29, s30, 0
	s_lshr_b32 s39, s39, 6
	v_lshl_or_b32 v132, s39, 14, v209
	s_add_i32 s42, s39, 4
	v_lshlrev_b64 v[128:129], 1, v[132:133]
	s_lshl_b32 s41, s39, 10
	v_lshl_or_b32 v132, s42, 14, v209
	v_lshl_add_u64 v[0:1], s[8:9], 0, v[128:129]
	s_mov_b32 m0, s41
	v_lshlrev_b64 v[130:131], 1, v[132:133]
	s_lshl_b32 s43, s42, 9
	s_lshl_b32 s42, s42, 10
	s_add_i32 s44, s39, 8
	global_load_lds_dwordx4 v[0:1], off
	v_lshl_add_u64 v[2:3], s[8:9], 0, v[130:131]
	s_mov_b32 m0, s42
	v_lshl_or_b32 v132, s44, 14, v209
	s_lshl_b32 s45, s44, 9
	s_lshl_b32 s44, s44, 10
	s_add_i32 s46, s39, 12
	global_load_lds_dwordx4 v[2:3], off
	v_lshl_add_u64 v[4:5], v[132:133], 1, s[8:9]
	s_mov_b32 m0, s44
	v_lshl_or_b32 v140, s46, 14, v209
	v_mov_b32_e32 v141, v133
	s_lshl_b32 s47, s46, 9
	s_lshl_b32 s46, s46, 10
	global_load_lds_dwordx4 v[4:5], off
	v_lshl_add_u64 v[6:7], v[140:141], 1, s[8:9]
	s_mov_b32 m0, s46
	v_lshl_add_u64 v[8:9], s[28:29], 0, v[128:129]
	global_load_lds_dwordx4 v[6:7], off
	s_add_i32 m0, s41, 0x4000
	v_lshl_add_u64 v[10:11], s[28:29], 0, v[130:131]
	global_load_lds_dwordx4 v[8:9], off
	s_add_i32 m0, s42, 0x4000
	v_lshl_add_u64 v[0:1], v[0:1], 0, 64
	global_load_lds_dwordx4 v[10:11], off
	s_add_i32 m0, s41, 0x6000
	s_lshl_b32 s40, s39, 9
	global_load_lds_dwordx4 v[0:1], off
	v_lshl_add_u64 v[0:1], v[2:3], 0, 64
	s_add_i32 m0, s42, 0x6000
	s_lshl_b32 s39, s39, 11
	global_load_lds_dwordx4 v[0:1], off
	v_lshl_add_u64 v[0:1], v[4:5], 0, 64
	s_add_i32 m0, s44, 0x6000
	s_lshl_b32 s40, s40, 1
	global_load_lds_dwordx4 v[0:1], off
	v_lshl_add_u64 v[0:1], v[6:7], 0, 64
	s_add_i32 m0, s46, 0x6000
	v_mov_b32_e32 v139, v133
	global_load_lds_dwordx4 v[0:1], off
	v_lshl_add_u64 v[0:1], v[8:9], 0, 64
	s_add_i32 m0, s41, 0xa000
	s_lshl_b32 s41, s43, 1
	global_load_lds_dwordx4 v[0:1], off
	v_lshl_add_u64 v[0:1], v[10:11], 0, 64
	s_add_i32 m0, s42, 0xa000
	s_lshl_b32 s42, s45, 1
	global_load_lds_dwordx4 v[0:1], off
	s_lshl_b32 s43, s47, 1
	s_mov_b32 s44, 0
	s_mov_b32 s45, 0
	v_mov_b32_e32 v48, v133
	v_mov_b32_e32 v49, v133
	v_mov_b32_e32 v50, v133
	v_mov_b32_e32 v51, v133
	v_mov_b32_e32 v52, v133
	v_mov_b32_e32 v53, v133
	v_mov_b32_e32 v54, v133
	v_mov_b32_e32 v55, v133
	v_mov_b32_e32 v56, v133
	v_mov_b32_e32 v57, v133
	v_mov_b32_e32 v58, v133
	v_mov_b32_e32 v59, v133
	v_mov_b32_e32 v60, v133
	v_mov_b32_e32 v61, v133
	v_mov_b32_e32 v62, v133
	v_mov_b32_e32 v63, v133
	v_mov_b32_e32 v80, v133
	v_mov_b32_e32 v81, v133
	v_mov_b32_e32 v82, v133
	v_mov_b32_e32 v83, v133
	v_mov_b32_e32 v84, v133
	v_mov_b32_e32 v85, v133
	v_mov_b32_e32 v86, v133
	v_mov_b32_e32 v87, v133
	v_mov_b32_e32 v88, v133
	v_mov_b32_e32 v89, v133
	v_mov_b32_e32 v90, v133
	v_mov_b32_e32 v91, v133
	v_mov_b32_e32 v92, v133
	v_mov_b32_e32 v93, v133
	v_mov_b32_e32 v94, v133
	v_mov_b32_e32 v95, v133
	v_mov_b32_e32 v96, v133
	v_mov_b32_e32 v97, v133
	v_mov_b32_e32 v98, v133
	v_mov_b32_e32 v99, v133
	v_mov_b32_e32 v100, v133
	v_mov_b32_e32 v101, v133
	v_mov_b32_e32 v102, v133
	v_mov_b32_e32 v103, v133
	v_mov_b32_e32 v104, v133
	v_mov_b32_e32 v105, v133
	v_mov_b32_e32 v106, v133
	v_mov_b32_e32 v107, v133
	v_mov_b32_e32 v108, v133
	v_mov_b32_e32 v109, v133
	v_mov_b32_e32 v110, v133
	v_mov_b32_e32 v111, v133
	v_mov_b32_e32 v112, v133
	v_mov_b32_e32 v113, v133
	v_mov_b32_e32 v114, v133
	v_mov_b32_e32 v115, v133
	v_mov_b32_e32 v116, v133
	v_mov_b32_e32 v117, v133
	v_mov_b32_e32 v118, v133
	v_mov_b32_e32 v119, v133
	v_mov_b32_e32 v120, v133
	v_mov_b32_e32 v121, v133
	v_mov_b32_e32 v122, v133
	v_mov_b32_e32 v123, v133
	v_mov_b32_e32 v124, v133
	v_mov_b32_e32 v125, v133
	v_mov_b32_e32 v126, v133
	v_mov_b32_e32 v127, v133
	v_mov_b32_e32 v0, v133
	v_mov_b32_e32 v1, v133
	v_mov_b32_e32 v2, v133
	v_mov_b32_e32 v3, v133
	v_mov_b32_e32 v4, v133
	v_mov_b32_e32 v5, v133
	v_mov_b32_e32 v6, v133
	v_mov_b32_e32 v7, v133
	v_mov_b32_e32 v8, v133
	v_mov_b32_e32 v9, v133
	v_mov_b32_e32 v10, v133
	v_mov_b32_e32 v11, v133
	v_mov_b32_e32 v12, v133
	v_mov_b32_e32 v13, v133
	v_mov_b32_e32 v14, v133
	v_mov_b32_e32 v15, v133
	v_mov_b32_e32 v16, v133
	v_mov_b32_e32 v17, v133
	v_mov_b32_e32 v18, v133
	v_mov_b32_e32 v19, v133
	v_mov_b32_e32 v20, v133
	v_mov_b32_e32 v21, v133
	v_mov_b32_e32 v22, v133
	v_mov_b32_e32 v23, v133
	v_mov_b32_e32 v24, v133
	v_mov_b32_e32 v25, v133
	v_mov_b32_e32 v26, v133
	v_mov_b32_e32 v27, v133
	v_mov_b32_e32 v28, v133
	v_mov_b32_e32 v29, v133
	v_mov_b32_e32 v30, v133
	v_mov_b32_e32 v31, v133
	v_mov_b32_e32 v32, v133
	v_mov_b32_e32 v33, v133
	v_mov_b32_e32 v34, v133
	v_mov_b32_e32 v35, v133
	v_mov_b32_e32 v36, v133
	v_mov_b32_e32 v37, v133
	v_mov_b32_e32 v38, v133
	v_mov_b32_e32 v39, v133
	v_mov_b32_e32 v40, v133
	v_mov_b32_e32 v41, v133
	v_mov_b32_e32 v42, v133
	v_mov_b32_e32 v43, v133
	v_mov_b32_e32 v44, v133
	v_mov_b32_e32 v45, v133
	v_mov_b32_e32 v46, v133
	v_mov_b32_e32 v47, v133
	v_mov_b32_e32 v64, v133
	v_mov_b32_e32 v65, v133
	v_mov_b32_e32 v66, v133
	v_mov_b32_e32 v67, v133
	v_mov_b32_e32 v68, v133
	v_mov_b32_e32 v69, v133
	v_mov_b32_e32 v70, v133
	v_mov_b32_e32 v71, v133
	v_mov_b32_e32 v72, v133
	v_mov_b32_e32 v73, v133
	v_mov_b32_e32 v74, v133
	v_mov_b32_e32 v75, v133
	v_mov_b32_e32 v76, v133
	v_mov_b32_e32 v77, v133
	v_mov_b32_e32 v78, v133
	v_mov_b32_e32 v79, v133

; DI void glds2_stage(const u16* __restrict__ Wb, int K, const u16* __restrict__ Tb, int ldt, int k0, u16* lds, int w, int lane) {
;   const int rsub = lane >> 2;
; #pragma unroll
;   for (int i = 0; i < 4; ++i) {
;     const int grp = w + 4 * i;
;     const int row = grp * 16 + rsub;
;     const int c = (lane & 3) ^ ((row >> 2) & 3);
;     const unsigned off = (unsigned)(row * K + c * 8);
;     __builtin_amdgcn_global_load_lds((const unsigned*)(Wb + k0 + (size_t)off), (unsigned*)(lds + grp * 512), 16, 0, 0);
;   }
; #pragma unroll
;   for (int i = 0; i < 2; ++i) {
;     const int grp = w + 4 * i;
;     const int row = grp * 16 + rsub;
;     const int c = (lane & 3) ^ ((row >> 2) & 3);
;     const unsigned off = (unsigned)(row * ldt + c * 8);
;     __builtin_amdgcn_global_load_lds((const unsigned*)(Tb + k0 + (size_t)off), (unsigned*)(lds + 8192 + grp * 512), 16, 0, 0);
;   }
; }
; template <bool CT, bool MID, bool SSQ = false>
; DI void gemm2(f32x16 (&accA)[4], f32x16 (&accB)[4], const u16* __restrict__ Wb, const u16* __restrict__ Tb, int ldt, int K,
;               u16* smem, const float* s_mid, float* ssq_out = nullptr) {
;   float ssq_acc = 0.f;
;   const int tid = threadIdx.x, lane = tid & 63, w = __builtin_amdgcn_readfirstlane(tid >> 6), r = lane & 31, h = lane >> 5;
; #pragma unroll
;   for (int m = 0; m < 4; ++m) { accA[m] = zero16(); accB[m] = zero16(); }
;   const int nk = K / 32;
;   asm volatile("s_waitcnt vmcnt(0)" ::: "memory");
;   glds2_stage(Wb, K, Tb, ldt, 0, smem, w, lane);
;   glds2_stage(Wb, K, Tb, ldt, 32, smem + G2_STAGE, w, lane);
;   const int swr = (r >> 2) & 3;
.LBB0_337:
	s_lshl_b32 s21, s20, 1
	s_and_b32 s21, s21, 0x3f8
	s_and_b32 s65, s20, 3
	s_or_b32 s64, s21, s55
	s_lshl_b32 s20, s65, 18
	s_add_u32 s20, s26, s20
	s_addc_u32 s21, s27, 0
	s_lshl_b32 s22, s64, 17
	s_add_u32 s22, s24, s22
	v_readfirstlane_b32 s66, v188
	s_addc_u32 s23, s25, 0
	s_lshr_b32 s67, s66, 6
	v_lshl_or_b32 v128, s67, 13, v144
	s_add_i32 s70, s67, 4
	v_lshlrev_b64 v[130:131], 1, v[128:129]
	s_lshl_b32 s69, s67, 10
	v_lshl_or_b32 v128, s70, 13, v144
	v_lshl_add_u64 v[0:1], s[20:21], 0, v[130:131]
	s_mov_b32 m0, s69
	v_lshlrev_b64 v[132:133], 1, v[128:129]
	s_lshl_b32 s71, s70, 9
	s_lshl_b32 s70, s70, 10
	s_add_i32 s72, s67, 8
	s_lshl_b32 s68, s67, 9
	global_load_lds_dwordx4 v[0:1], off
	v_lshl_add_u64 v[2:3], s[20:21], 0, v[132:133]
	s_mov_b32 m0, s70
	v_lshl_or_b32 v128, s72, 13, v144
	s_lshl_b32 s73, s72, 9
	s_lshl_b32 s72, s72, 10
	s_add_i32 s67, s67, 12
	global_load_lds_dwordx4 v[2:3], off
	v_lshl_add_u64 v[4:5], v[128:129], 1, s[20:21]
	s_mov_b32 m0, s72
	v_lshl_or_b32 v6, s67, 13, v144
	v_mov_b32_e32 v7, v129
	s_lshl_b32 s74, s67, 9
	s_lshl_b32 s67, s67, 10
	global_load_lds_dwordx4 v[4:5], off
	v_lshl_add_u64 v[8:9], v[6:7], 1, s[20:21]
	s_mov_b32 m0, s67
	v_lshl_add_u64 v[10:11], s[22:23], 0, v[130:131]
	global_load_lds_dwordx4 v[8:9], off
	s_add_i32 m0, s69, 0x4000
	v_lshl_add_u64 v[12:13], s[22:23], 0, v[132:133]
	global_load_lds_dwordx4 v[10:11], off
	s_add_i32 m0, s70, 0x4000
	v_lshl_add_u64 v[0:1], v[0:1], 0, 64
	global_load_lds_dwordx4 v[12:13], off
	s_add_i32 m0, s69, 0x6000
	s_lshl_b32 s66, s66, 5
	global_load_lds_dwordx4 v[0:1], off
	v_lshl_add_u64 v[0:1], v[2:3], 0, 64
	s_add_i32 m0, s70, 0x6000
	v_lshlrev_b64 v[134:135], 1, v[128:129]
	global_load_lds_dwordx4 v[0:1], off
	v_lshl_add_u64 v[0:1], v[4:5], 0, 64
	s_add_i32 m0, s72, 0x6000
	v_lshlrev_b64 v[136:137], 1, v[6:7]
	global_load_lds_dwordx4 v[0:1], off
	v_lshl_add_u64 v[0:1], v[8:9], 0, 64
	s_add_i32 m0, s67, 0x6000
	s_lshl_b32 s67, s71, 1
	global_load_lds_dwordx4 v[0:1], off
	v_lshl_add_u64 v[0:1], v[10:11], 0, 64
	s_add_i32 m0, s69, 0xa000
	s_lshl_b32 s69, s74, 1
	global_load_lds_dwordx4 v[0:1], off
	v_lshl_add_u64 v[0:1], v[12:13], 0, 64
	s_add_i32 m0, s70, 0xa000
	s_and_b32 s70, s66, 0xfffff800
	global_load_lds_dwordx4 v[0:1], off
	s_lshl_b32 s66, s68, 1
	s_lshl_b32 s68, s73, 1
	s_lshl_b32 s70, s70, 1
	s_mov_b32 s72, 0
	s_mov_b32 s71, 0
	v_mov_b32_e32 v0, 0
	v_mov_b32_e32 v1, v129
	v_mov_b32_e32 v2, v129
	v_mov_b32_e32 v3, v129
	v_mov_b32_e32 v4, v129
	v_mov_b32_e32 v5, v129
	v_mov_b32_e32 v6, v129
	v_mov_b32_e32 v8, v129
	v_mov_b32_e32 v9, v129
	v_mov_b32_e32 v10, v129
	v_mov_b32_e32 v11, v129
	v_mov_b32_e32 v12, v129
	v_mov_b32_e32 v13, v129
	v_mov_b32_e32 v14, v129
	v_mov_b32_e32 v15, v129
	v_mov_b32_e32 v32, 0
	v_mov_b32_e32 v33, v129
	v_mov_b32_e32 v34, v129
	v_mov_b32_e32 v35, v129
	v_mov_b32_e32 v36, v129
	v_mov_b32_e32 v37, v129
	v_mov_b32_e32 v38, v129
	v_mov_b32_e32 v39, v129
	v_mov_b32_e32 v40, v129
	v_mov_b32_e32 v41, v129
	v_mov_b32_e32 v42, v129
	v_mov_b32_e32 v43, v129
	v_mov_b32_e32 v44, v129
	v_mov_b32_e32 v45, v129
	v_mov_b32_e32 v46, v129
	v_mov_b32_e32 v47, v129
	v_mov_b32_e32 v64, 0
	v_mov_b32_e32 v65, v129
	v_mov_b32_e32 v66, v129
	v_mov_b32_e32 v67, v129
	v_mov_b32_e32 v68, v129
	v_mov_b32_e32 v69, v129
	v_mov_b32_e32 v70, v129
	v_mov_b32_e32 v71, v129
	v_mov_b32_e32 v72, v129
	v_mov_b32_e32 v73, v129
	v_mov_b32_e32 v74, v129
	v_mov_b32_e32 v75, v129
	v_mov_b32_e32 v76, v129
	v_mov_b32_e32 v77, v129
	v_mov_b32_e32 v78, v129
	v_mov_b32_e32 v79, v129
	v_mov_b32_e32 v96, 0
	v_mov_b32_e32 v97, v129
	v_mov_b32_e32 v98, v129
	v_mov_b32_e32 v99, v129
	v_mov_b32_e32 v100, v129
	v_mov_b32_e32 v101, v129
	v_mov_b32_e32 v102, v129
	v_mov_b32_e32 v103, v129
	v_mov_b32_e32 v104, v129
	v_mov_b32_e32 v105, v129
	v_mov_b32_e32 v106, v129
	v_mov_b32_e32 v107, v129
	v_mov_b32_e32 v108, v129
	v_mov_b32_e32 v109, v129
	v_mov_b32_e32 v110, v129
	v_mov_b32_e32 v111, v129
	v_mov_b32_e32 v16, 0
	v_mov_b32_e32 v17, v129
	v_mov_b32_e32 v18, v129
	v_mov_b32_e32 v19, v129
	v_mov_b32_e32 v20, v129
	v_mov_b32_e32 v21, v129
	v_mov_b32_e32 v22, v129
	v_mov_b32_e32 v23, v129
	v_mov_b32_e32 v24, v129
	v_mov_b32_e32 v25, v129
	v_mov_b32_e32 v26, v129
	v_mov_b32_e32 v27, v129
	v_mov_b32_e32 v28, v129
	v_mov_b32_e32 v29, v129
	v_mov_b32_e32 v30, v129
	v_mov_b32_e32 v31, v129
	v_mov_b32_e32 v48, 0
	v_mov_b32_e32 v49, v129
	v_mov_b32_e32 v50, v129
	v_mov_b32_e32 v51, v129
	v_mov_b32_e32 v52, v129
	v_mov_b32_e32 v53, v129
	v_mov_b32_e32 v54, v129
	v_mov_b32_e32 v55, v129
	v_mov_b32_e32 v56, v129
	v_mov_b32_e32 v57, v129
	v_mov_b32_e32 v58, v129
	v_mov_b32_e32 v59, v129
	v_mov_b32_e32 v60, v129
	v_mov_b32_e32 v61, v129
	v_mov_b32_e32 v62, v129
	v_mov_b32_e32 v63, v129
	v_mov_b32_e32 v80, 0
	v_mov_b32_e32 v81, v129
	v_mov_b32_e32 v82, v129
	v_mov_b32_e32 v83, v129
	v_mov_b32_e32 v84, v129
	v_mov_b32_e32 v85, v129
	v_mov_b32_e32 v86, v129
	v_mov_b32_e32 v87, v129
	v_mov_b32_e32 v88, v129
	v_mov_b32_e32 v89, v129
	v_mov_b32_e32 v90, v129
	v_mov_b32_e32 v91, v129
	v_mov_b32_e32 v92, v129
	v_mov_b32_e32 v93, v129
	v_mov_b32_e32 v94, v129
	v_mov_b32_e32 v95, v129
	v_mov_b32_e32 v112, 0
	v_mov_b32_e32 v113, v129
	v_mov_b32_e32 v114, v129
	v_mov_b32_e32 v115, v129
	v_mov_b32_e32 v116, v129
	v_mov_b32_e32 v117, v129
	v_mov_b32_e32 v118, v129
	v_mov_b32_e32 v119, v129
	v_mov_b32_e32 v120, v129
	v_mov_b32_e32 v121, v129
	v_mov_b32_e32 v122, v129
	v_mov_b32_e32 v123, v129
	v_mov_b32_e32 v124, v129
	v_mov_b32_e32 v125, v129
	v_mov_b32_e32 v126, v129
	v_mov_b32_e32 v127, v129

; DI void glds2_stage(const u16* __restrict__ Wb, int K, const u16* __restrict__ Tb, int ldt, int k0, u16* lds, int w, int lane) {
;   const int rsub = lane >> 2;
; #pragma unroll
;   for (int i = 0; i < 4; ++i) {
;     const int grp = w + 4 * i;
;     const int row = grp * 16 + rsub;
;     const int c = (lane & 3) ^ ((row >> 2) & 3);
;     const unsigned off = (unsigned)(row * K + c * 8);
;     __builtin_amdgcn_global_load_lds((const unsigned*)(Wb + k0 + (size_t)off), (unsigned*)(lds + grp * 512), 16, 0, 0);
;   }
; #pragma unroll
;   for (int i = 0; i < 2; ++i) {
;     const int grp = w + 4 * i;
;     const int row = grp * 16 + rsub;
;     const int c = (lane & 3) ^ ((row >> 2) & 3);
;     const unsigned off = (unsigned)(row * ldt + c * 8);
;     __builtin_amdgcn_global_load_lds((const unsigned*)(Tb + k0 + (size_t)off), (unsigned*)(lds + 8192 + grp * 512), 16, 0, 0);
;   }
; }
; DI void gemm2_f8(f32x16 (&accA)[4], f32x16 (&accB)[4], const unsigned char* __restrict__ Wb, const unsigned char* __restrict__ Tb,
;                  int K  , u16* smem) {
;   const int tid = threadIdx.x, lane = tid & 63, w = __builtin_amdgcn_readfirstlane(tid >> 6), r = lane & 31, h = lane >> 5;
; #pragma unroll
;   for (int m = 0; m < 4; ++m) { accA[m] = zero16(); accB[m] = zero16(); }
;   const int K2 = K >> 1;
;   const int nk = K2 / 32;
;   const u16* W16 = (const u16*)Wb; const u16* T16 = (const u16*)Tb;
;   asm volatile("s_waitcnt vmcnt(0)" ::: "memory");
;   glds2_stage(W16, K2, T16, K2, 0, smem, w, lane);
;   glds2_stage(W16, K2, T16, K2, 32, smem + G2_STAGE, w, lane);
;   const int swr = (r >> 2) & 3;
;   int st = 0;
.LBB0_359:
	s_and_b32 s28, s10, 0x3f8
	s_and_b32 s81, s10, 7
	s_or_b32 s82, s28, s55
	s_lshl_b32 s10, s81, 18
	s_add_u32 s28, s13, s10
	s_addc_u32 s29, s27, 0
	s_lshl_b32 s10, s82, 17
	s_add_u32 s30, s34, s10
	v_readfirstlane_b32 s10, v188
	s_addc_u32 s31, s35, 0
	s_lshr_b32 s10, s10, 6
	v_lshl_or_b32 v132, s10, 13, v158
	s_add_i32 s85, s10, 4
	v_lshlrev_b64 v[128:129], 1, v[132:133]
	s_lshl_b32 s84, s10, 10
	v_lshl_or_b32 v132, s85, 13, v158
	v_lshl_add_u64 v[0:1], s[28:29], 0, v[128:129]
	s_mov_b32 m0, s84
	v_lshlrev_b64 v[130:131], 1, v[132:133]
	s_lshl_b32 s86, s85, 9
	s_lshl_b32 s85, s85, 10
	s_add_i32 s87, s10, 8
	global_load_lds_dwordx4 v[0:1], off
	v_lshl_add_u64 v[2:3], s[28:29], 0, v[130:131]
	s_mov_b32 m0, s85
	v_lshl_or_b32 v132, s87, 13, v158
	s_lshl_b32 s88, s87, 9
	s_lshl_b32 s87, s87, 10
	s_add_i32 s89, s10, 12
	global_load_lds_dwordx4 v[2:3], off
	v_lshl_add_u64 v[4:5], v[132:133], 1, s[28:29]
	s_mov_b32 m0, s87
	v_lshl_or_b32 v154, s89, 13, v158
	v_mov_b32_e32 v155, v133
	s_lshl_b32 s90, s89, 9
	s_lshl_b32 s89, s89, 10
	global_load_lds_dwordx4 v[4:5], off
	v_lshl_add_u64 v[6:7], v[154:155], 1, s[28:29]
	s_mov_b32 m0, s89
	v_lshl_add_u64 v[8:9], s[30:31], 0, v[128:129]
	global_load_lds_dwordx4 v[6:7], off
	s_add_i32 m0, s84, 0x4000
	v_lshl_add_u64 v[10:11], s[30:31], 0, v[130:131]
	global_load_lds_dwordx4 v[8:9], off
	s_add_i32 m0, s85, 0x4000
	v_lshl_add_u64 v[0:1], v[0:1], 0, 64
	global_load_lds_dwordx4 v[10:11], off
	s_add_i32 m0, s84, 0x6000
	s_lshl_b32 s83, s10, 9
	global_load_lds_dwordx4 v[0:1], off
	v_lshl_add_u64 v[0:1], v[2:3], 0, 64
	s_add_i32 m0, s85, 0x6000
	s_lshl_b32 s10, s10, 11
	global_load_lds_dwordx4 v[0:1], off
	v_lshl_add_u64 v[0:1], v[4:5], 0, 64
	s_add_i32 m0, s87, 0x6000
	s_lshl_b32 s83, s83, 1
	global_load_lds_dwordx4 v[0:1], off
	v_lshl_add_u64 v[0:1], v[6:7], 0, 64
	s_add_i32 m0, s89, 0x6000
	s_mov_b32 s87, 0
	global_load_lds_dwordx4 v[0:1], off
	v_lshl_add_u64 v[0:1], v[8:9], 0, 64
	s_add_i32 m0, s84, 0xa000
	s_lshl_b32 s84, s86, 1
	global_load_lds_dwordx4 v[0:1], off
	v_lshl_add_u64 v[0:1], v[10:11], 0, 64
	s_add_i32 m0, s85, 0xa000
	s_lshl_b32 s85, s88, 1
	global_load_lds_dwordx4 v[0:1], off
	s_lshl_b32 s86, s90, 1
	s_mov_b32 s88, 0
	v_mov_b32_e32 v0, v133
	v_mov_b32_e32 v1, v133
	v_mov_b32_e32 v2, v133
	v_mov_b32_e32 v3, v133
	v_mov_b32_e32 v4, v133
	v_mov_b32_e32 v5, v133
	v_mov_b32_e32 v6, v133
	v_mov_b32_e32 v7, v133
	v_mov_b32_e32 v8, v133
	v_mov_b32_e32 v9, v133
	v_mov_b32_e32 v10, v133
	v_mov_b32_e32 v11, v133
	v_mov_b32_e32 v12, v133
	v_mov_b32_e32 v13, v133
	v_mov_b32_e32 v14, v133
	v_mov_b32_e32 v15, v133
	v_mov_b32_e32 v16, v133
	v_mov_b32_e32 v17, v133
	v_mov_b32_e32 v18, v133
	v_mov_b32_e32 v19, v133
	v_mov_b32_e32 v20, v133
	v_mov_b32_e32 v21, v133
	v_mov_b32_e32 v22, v133
	v_mov_b32_e32 v23, v133
	v_mov_b32_e32 v24, v133
	v_mov_b32_e32 v25, v133
	v_mov_b32_e32 v26, v133
	v_mov_b32_e32 v27, v133
	v_mov_b32_e32 v28, v133
	v_mov_b32_e32 v29, v133
	v_mov_b32_e32 v30, v133
	v_mov_b32_e32 v31, v133
	v_mov_b32_e32 v48, v133
	v_mov_b32_e32 v49, v133
	v_mov_b32_e32 v50, v133
	v_mov_b32_e32 v51, v133
	v_mov_b32_e32 v52, v133
	v_mov_b32_e32 v53, v133
	v_mov_b32_e32 v54, v133
	v_mov_b32_e32 v55, v133
	v_mov_b32_e32 v56, v133
	v_mov_b32_e32 v57, v133
	v_mov_b32_e32 v58, v133
	v_mov_b32_e32 v59, v133
	v_mov_b32_e32 v60, v133
	v_mov_b32_e32 v61, v133
	v_mov_b32_e32 v62, v133
	v_mov_b32_e32 v63, v133
	v_mov_b32_e32 v80, v133
	v_mov_b32_e32 v81, v133
	v_mov_b32_e32 v82, v133
	v_mov_b32_e32 v83, v133
	v_mov_b32_e32 v84, v133
	v_mov_b32_e32 v85, v133
	v_mov_b32_e32 v86, v133
	v_mov_b32_e32 v87, v133
	v_mov_b32_e32 v88, v133
	v_mov_b32_e32 v89, v133
	v_mov_b32_e32 v90, v133
	v_mov_b32_e32 v91, v133
	v_mov_b32_e32 v92, v133
	v_mov_b32_e32 v93, v133
	v_mov_b32_e32 v94, v133
	v_mov_b32_e32 v95, v133
	v_mov_b32_e32 v32, v133
	v_mov_b32_e32 v33, v133
	v_mov_b32_e32 v34, v133
	v_mov_b32_e32 v35, v133
	v_mov_b32_e32 v36, v133
	v_mov_b32_e32 v37, v133
	v_mov_b32_e32 v38, v133
	v_mov_b32_e32 v39, v133
	v_mov_b32_e32 v40, v133
	v_mov_b32_e32 v41, v133
	v_mov_b32_e32 v42, v133
	v_mov_b32_e32 v43, v133
	v_mov_b32_e32 v44, v133
	v_mov_b32_e32 v45, v133
	v_mov_b32_e32 v46, v133
	v_mov_b32_e32 v47, v133
	v_mov_b32_e32 v64, v133
	v_mov_b32_e32 v65, v133
	v_mov_b32_e32 v66, v133
	v_mov_b32_e32 v67, v133
	v_mov_b32_e32 v68, v133
	v_mov_b32_e32 v69, v133
	v_mov_b32_e32 v70, v133
	v_mov_b32_e32 v71, v133
	v_mov_b32_e32 v72, v133
	v_mov_b32_e32 v73, v133
	v_mov_b32_e32 v74, v133
	v_mov_b32_e32 v75, v133
	v_mov_b32_e32 v76, v133
	v_mov_b32_e32 v77, v133
	v_mov_b32_e32 v78, v133
	v_mov_b32_e32 v79, v133
	v_mov_b32_e32 v96, v133
	v_mov_b32_e32 v97, v133
	v_mov_b32_e32 v98, v133
	v_mov_b32_e32 v99, v133
	v_mov_b32_e32 v100, v133
	v_mov_b32_e32 v101, v133
	v_mov_b32_e32 v102, v133
	v_mov_b32_e32 v103, v133
	v_mov_b32_e32 v104, v133
	v_mov_b32_e32 v105, v133
	v_mov_b32_e32 v106, v133
	v_mov_b32_e32 v107, v133
	v_mov_b32_e32 v108, v133
	v_mov_b32_e32 v109, v133
	v_mov_b32_e32 v110, v133
	v_mov_b32_e32 v111, v133
	v_mov_b32_e32 v112, v133
	v_mov_b32_e32 v113, v133
	v_mov_b32_e32 v114, v133
	v_mov_b32_e32 v115, v133
	v_mov_b32_e32 v116, v133
	v_mov_b32_e32 v117, v133
	v_mov_b32_e32 v118, v133
	v_mov_b32_e32 v119, v133
	v_mov_b32_e32 v120, v133
	v_mov_b32_e32 v121, v133
	v_mov_b32_e32 v122, v133
	v_mov_b32_e32 v123, v133
	v_mov_b32_e32 v124, v133
	v_mov_b32_e32 v125, v133
	v_mov_b32_e32 v126, v133
	v_mov_b32_e32 v127, v133

; DI void phase5b3(const Params& p, u16* smem) {
;   unsigned char* ws = p.ws;
;   const int tid = threadIdx.x, lane = tid & 63, w = __builtin_amdgcn_readfirstlane(tid >> 6), rsub = lane >> 3, ch = lane & 7;
;   const int G8 = gridDim.x >> 3;
;   if ((int)blockIdx.x >= 8 * G8) return;
;   const int slice = blockIdx.x & 7, rank = blockIdx.x >> 3;
;   const unsigned char* V8 = ws + OFF_V8 + (size_t)slice * 16384 * 128;
;   const unsigned choff = ch * 16;
;   const unsigned* pw = (const unsigned*)(ws + OFF_PW);
;   unsigned* scr = (unsigned*)smem + w * 128;
;   const int stride = G8 * 4;
;   int t = rank * 4 + w;
;   if (t >= T_ALL) return;
;   auto clampt = [&](int x) __attribute__((always_inline)) { return x < T_ALL ? x : t; };
;   auto gload = [&](int tt) __attribute__((always_inline)) { return *(const uint2*)(pw + (size_t)(unsigned)(tt * 128 + lane * 2)); };
;   unsigned kA[16], kB[16];
;   uint4 vA[16], vB[16];
;   uint2 pX = gload(clampt(t + stride)), pY = gload(clampt(t + 2 * stride));
;   p5b3_redist(kA, gload(t), scr, lane, rsub);
;   p5b3_load_v(vA, kA, V8, choff);
;   for (;;) {
.LBB0_420:
	s_or_b64 exec, exec, s[8:9]
	s_and_b64 vcc, exec, s[4:5]
	v_readfirstlane_b32 s3, v188
	s_barrier
	s_barrier
	s_cbranch_vccnz .LBB0_430
	s_lshr_b32 s2, s2, 1
	s_lshr_b32 s10, s3, 6
	s_and_b32 s2, s2, 0x7ffffffc
	s_add_i32 s16, s10, s2
	s_cmp_gt_u32 s16, 0x17fff
	s_cbranch_scc1 .LBB0_430
	s_load_dwordx4 s[4:7], s[0:1], 0xd8
	s_lshl_b32 s0, s55, 21
	v_lshlrev_b32_e32 v166, 1, v195
	v_mov_b32_e32 v129, 0
	s_waitcnt lgkmcnt(0)
	s_add_u32 s0, s6, s0
	s_addc_u32 s1, s7, 0
	s_add_u32 s2, s0, 0x1d80000
	s_addc_u32 s3, s1, 0
	s_add_u32 s8, s6, 0x9188000
	s_addc_u32 s9, s7, 0
	s_lshr_b32 s0, s12, 1
	s_and_b32 s12, s0, 0x7ffffffc
	s_lshl_b32 s1, s10, 9
	s_add_i32 s11, s16, s12
	s_cmp_lt_u32 s11, 0x18000
	s_cselect_b32 s0, s11, s16
	v_lshl_or_b32 v128, s0, 7, v166
	s_add_i32 s0, s11, s12
	s_cmp_lt_u32 s0, 0x18000
	s_cselect_b32 s0, s0, s16
	v_lshl_add_u64 v[0:1], v[128:129], 2, s[8:9]
	v_lshl_or_b32 v128, s0, 7, v166
	v_lshl_add_u64 v[2:3], v[128:129], 2, s[8:9]
	v_lshl_or_b32 v128, s16, 7, v166
	v_lshl_add_u64 v[4:5], v[128:129], 2, s[8:9]
	global_load_dwordx2 v[6:7], v[4:5], off
	global_load_dwordx2 v[132:133], v[0:1], off
	global_load_dwordx2 v[130:131], v[2:3], off
	v_lshl_or_b32 v168, v195, 3, s1
	v_lshl_or_b32 v169, v191, 2, s1
	v_lshlrev_b32_e32 v0, 4, v188
	v_and_b32_e32 v167, 0x70, v0
	s_add_u32 s6, s6, 0x22888000
	s_addc_u32 s7, s7, 0
	s_lshl_b32 s14, s54, 12
	s_lshl_b32 s10, s10, 10
	s_lshl_b32 s17, s55, 7
	s_add_i32 s14, s14, s10
	s_lshl_b32 s11, s11, 10
	s_or_b32 s10, s14, s17
	s_or_b32 s11, s11, s17
	s_mul_i32 s13, s12, 3
	v_cmp_gt_u32_e64 s[0:1], 8, v195
	s_lshl_b32 s14, s33, 13
	s_lshl_b32 s15, s33, 4
	v_mov_b32_e32 v172, s11
	v_mov_b32_e32 v173, s10
	s_waitcnt vmcnt(2)
	ds_write_b64 v168, v[6:7]
	ds_read2_b32 v[148:149], v169 offset1:8
	ds_read2_b32 v[146:147], v169 offset0:16 offset1:24
	ds_read2_b32 v[144:145], v169 offset0:32 offset1:40
	ds_read2_b32 v[142:143], v169 offset0:48 offset1:56
	ds_read2_b32 v[140:141], v169 offset0:64 offset1:72
	ds_read2_b32 v[138:139], v169 offset0:80 offset1:88
	ds_read2_b32 v[136:137], v169 offset0:96 offset1:104
	ds_read2_b32 v[134:135], v169 offset0:112 offset1:120
	s_waitcnt lgkmcnt(7)
	v_bfe_u32 v0, v148, 16, 16
	s_waitcnt lgkmcnt(3)
	v_bfe_u32 v8, v140, 16, 16
	v_bfe_u32 v9, v141, 16, 16
	s_waitcnt lgkmcnt(2)
	v_bfe_u32 v10, v138, 16, 16
	v_bfe_u32 v11, v139, 16, 16
	v_bfe_u32 v1, v149, 16, 16
	v_bfe_u32 v2, v146, 16, 16
	v_bfe_u32 v3, v147, 16, 16
	v_bfe_u32 v4, v144, 16, 16
	v_bfe_u32 v5, v145, 16, 16
	v_bfe_u32 v6, v142, 16, 16
	v_bfe_u32 v7, v143, 16, 16
	s_waitcnt lgkmcnt(1)
	v_bfe_u32 v12, v136, 16, 16
	v_bfe_u32 v13, v137, 16, 16
	s_waitcnt lgkmcnt(0)
	v_bfe_u32 v14, v134, 16, 16
	v_bfe_u32 v15, v135, 16, 16
	v_lshl_or_b32 v60, v0, 7, v167
	v_lshl_or_b32 v8, v8, 7, v167
	v_lshl_or_b32 v9, v9, 7, v167
	v_lshl_or_b32 v10, v10, 7, v167
	v_lshl_or_b32 v11, v11, 7, v167
	v_lshl_or_b32 v61, v1, 7, v167
	v_lshl_or_b32 v62, v2, 7, v167
	v_lshl_or_b32 v63, v3, 7, v167
	v_lshl_or_b32 v64, v4, 7, v167
	v_lshl_or_b32 v65, v5, 7, v167
	v_lshl_or_b32 v66, v6, 7, v167
	v_lshl_or_b32 v67, v7, 7, v167
	v_lshl_or_b32 v68, v12, 7, v167
	v_lshl_or_b32 v69, v13, 7, v167
	v_lshl_or_b32 v70, v14, 7, v167
	v_lshl_or_b32 v71, v15, 7, v167
	global_load_dwordx4 v[72:75], v60, s[2:3]
	global_load_dwordx4 v[56:59], v61, s[2:3]
	global_load_dwordx4 v[52:55], v62, s[2:3]
	global_load_dwordx4 v[48:51], v63, s[2:3]
	global_load_dwordx4 v[44:47], v64, s[2:3]
	global_load_dwordx4 v[40:43], v65, s[2:3]
	global_load_dwordx4 v[36:39], v66, s[2:3]
	global_load_dwordx4 v[32:35], v67, s[2:3]
	global_load_dwordx4 v[12:15], v8, s[2:3]
	global_load_dwordx4 v[4:7], v9, s[2:3]
	global_load_dwordx4 v[0:3], v10, s[2:3]
	global_load_dwordx4 v[24:27], v11, s[2:3]
	global_load_dwordx4 v[16:19], v68, s[2:3]
	global_load_dwordx4 v[28:31], v69, s[2:3]
	global_load_dwordx4 v[20:23], v70, s[2:3]
	s_nop 0
	global_load_dwordx4 v[8:11], v71, s[2:3]
	v_and_b32_e32 v61, 64, v198
	v_xor_b32_e32 v60, 16, v198
	v_add_u32_e32 v61, 64, v61
	v_cmp_lt_i32_e32 vcc, v60, v61
	s_nop 1
	v_cndmask_b32_e32 v60, v198, v60, vcc
	v_lshlrev_b32_e32 v170, 2, v60
	v_xor_b32_e32 v60, 32, v198
	v_cmp_lt_i32_e32 vcc, v60, v61
	s_nop 1
	v_cndmask_b32_e32 v60, v198, v60, vcc
	v_lshlrev_b32_e32 v171, 2, v60
	s_waitcnt vmcnt(0)
	s_branch .LBB0_425

; DI void p5b3_load_v(uint4 (&vr)[16], const unsigned (&pk)[16], const unsigned char* V8, unsigned choff) {
; #pragma unroll
;   for (int i = 0; i < 16; ++i) vr[i] = *(const uint4*)(V8 + (size_t)(unsigned)(((pk[i] >> 16) << 7) + choff));
; }
; DI void p5b3_compute(const uint4 (&vr)[16], const unsigned (&pk)[16], float* outp, const u16* xres, int t, int slice, int rsub, int ch) {
;   float o[16];
; #pragma unroll
;   for (int i = 0; i < 16; ++i) o[i] = 0.f;
; #pragma unroll
;   for (int i = 0; i < 16; ++i) {
;     const unsigned vv[4] = {vr[i].x, vr[i].y, vr[i].z, vr[i].w};
;     const float wc = __uint_as_float(pk[i] << 16);
; #pragma unroll
;     for (int j = 0; j < 4; ++j) {
;       f32x2 lo = __builtin_amdgcn_cvt_pk_f32_fp8((int)vv[j], false);
;       f32x2 hi = __builtin_amdgcn_cvt_pk_f32_fp8((int)vv[j], true);
;       o[4 * j + 0] = fmaf(wc, lo[0], o[4 * j + 0]);
;       o[4 * j + 1] = fmaf(wc, lo[1], o[4 * j + 1]);
;       o[4 * j + 2] = fmaf(wc, hi[0], o[4 * j + 2]);
;       o[4 * j + 3] = fmaf(wc, hi[1], o[4 * j + 3]);
;     }
;   }
; DI void phase5b3(const Params& p, u16* smem) {
;     ...
;   for (;;) {
;     p5b3_redist(kB, pX, scr, lane, rsub);
;     p5b3_load_v(vB, kB, V8, choff);
;     pX = gload(clampt(t + 3 * stride));
;     p5b3_compute(vA, kA, p.out, (const u16*)(ws + OFF_XB), t, slice, rsub, ch);
.LBB0_425:
	s_waitcnt vmcnt(4)
	ds_write_b64 v168, v[132:133]
	ds_read2_b32 v[164:165], v169 offset1:8
	ds_read2_b32 v[162:163], v169 offset0:16 offset1:24
	ds_read2_b32 v[160:161], v169 offset0:32 offset1:40
	ds_read2_b32 v[158:159], v169 offset0:48 offset1:56
	ds_read2_b32 v[156:157], v169 offset0:64 offset1:72
	ds_read2_b32 v[154:155], v169 offset0:80 offset1:88
	ds_read2_b32 v[152:153], v169 offset0:96 offset1:104
	ds_read2_b32 v[150:151], v169 offset0:112 offset1:120
	s_waitcnt lgkmcnt(7)
	v_bfe_u32 v60, v164, 16, 16
	v_lshl_or_b32 v251, v60, 7, v167
	v_bfe_u32 v60, v165, 16, 16
	s_waitcnt lgkmcnt(6)
	v_bfe_u32 v61, v162, 16, 16
	v_lshl_or_b32 v60, v60, 7, v167
	v_lshl_or_b32 v61, v61, 7, v167
	global_load_dwordx4 v[120:123], v60, s[2:3]
	global_load_dwordx4 v[116:119], v61, s[2:3]
	v_bfe_u32 v60, v163, 16, 16
	s_waitcnt lgkmcnt(5)
	v_bfe_u32 v61, v160, 16, 16
	s_waitcnt lgkmcnt(2)
	v_bfe_u32 v76, v155, 16, 16
	s_add_i32 s10, s13, s16
	v_lshl_or_b32 v60, v60, 7, v167
	v_lshl_or_b32 v61, v61, 7, v167
	v_lshl_or_b32 v88, v76, 7, v167
	s_waitcnt lgkmcnt(1)
	v_bfe_u32 v76, v152, 16, 16
	s_cmp_lt_i32 s10, 0x18000
	global_load_dwordx4 v[112:115], v60, s[2:3]
	global_load_dwordx4 v[108:111], v61, s[2:3]
	v_bfe_u32 v60, v161, 16, 16
	v_bfe_u32 v61, v158, 16, 16
	v_lshl_or_b32 v250, v76, 7, v167
	s_waitcnt vmcnt(19)
	v_cvt_pk_f32_fp8_e32 v[76:77], v72
	s_cselect_b32 s10, s10, s16
	v_lshl_or_b32 v60, v60, 7, v167
	v_lshl_or_b32 v61, v61, 7, v167
	s_waitcnt vmcnt(18)
	v_cvt_pk_f32_fp8_e32 v[80:81], v56
	v_lshl_or_b32 v128, s10, 7, v166
	global_load_dwordx4 v[100:103], v60, s[2:3]
	global_load_dwordx4 v[92:95], v61, s[2:3]
	v_bfe_u32 v60, v159, 16, 16
	v_bfe_u32 v61, v156, 16, 16
	s_waitcnt vmcnt(19)
	v_cvt_pk_f32_fp8_e32 v[82:83], v52
	v_lshl_add_u64 v[174:175], v[128:129], 2, s[8:9]
	v_lshl_or_b32 v60, v60, 7, v167
	v_lshl_or_b32 v61, v61, 7, v167
	v_lshlrev_b32_e32 v128, 16, v148
	s_waitcnt vmcnt(18)
	v_cvt_pk_f32_fp8_e32 v[104:105], v48
	global_load_dwordx4 v[84:87], v60, s[2:3]
	global_load_dwordx4 v[68:71], v61, s[2:3]
	v_bfe_u32 v60, v157, 16, 16
	v_bfe_u32 v61, v154, 16, 16
	v_lshlrev_b32_e32 v148, 16, v149
	s_waitcnt vmcnt(19)
	v_cvt_pk_f32_fp8_e32 v[106:107], v44
	v_pk_fma_f32 v[76:77], v[128:129], v[76:77], 0 op_sel_hi:[0,1,0]
	v_lshl_or_b32 v60, v60, 7, v167
	v_lshl_or_b32 v61, v61, 7, v167
	v_lshlrev_b32_e32 v146, 16, v146
	s_waitcnt vmcnt(18)
	v_cvt_pk_f32_fp8_e32 v[132:133], v40
	v_pk_fma_f32 v[76:77], v[148:149], v[80:81], v[76:77] op_sel_hi:[0,1,1]
	global_load_dwordx4 v[64:67], v60, s[2:3]
	s_nop 0
	global_load_dwordx4 v[60:63], v61, s[2:3]
	s_waitcnt vmcnt(19)
	v_cvt_pk_f32_fp8_e32 v[226:227], v36
	v_pk_fma_f32 v[76:77], v[146:147], v[82:83], v[76:77] op_sel_hi:[0,1,1]
	global_load_dwordx4 v[88:91], v88, s[2:3]
	s_nop 0
	global_load_dwordx4 v[80:83], v250, s[2:3]
	v_lshlrev_b32_e32 v250, 16, v147
	s_waitcnt vmcnt(20)
	v_cvt_pk_f32_fp8_e32 v[238:239], v32
	v_pk_fma_f32 v[76:77], v[250:251], v[104:105], v[76:77] op_sel_hi:[0,1,1]
	v_lshlrev_b32_e32 v144, 16, v144
	s_waitcnt lgkmcnt(0)
	v_bfe_u32 v104, v150, 16, 16
	v_cvt_pk_f32_fp8_sdwa v[78:79], v72 src0_sel:WORD_1
	v_pk_fma_f32 v[76:77], v[144:145], v[106:107], v[76:77] op_sel_hi:[0,1,1]
	v_lshl_or_b32 v147, v104, 7, v167
	v_lshlrev_b32_e32 v252, 16, v145
	s_waitcnt vmcnt(19)
	v_cvt_pk_f32_fp8_e32 v[104:105], v12
	v_cvt_pk_f32_fp8_sdwa v[96:97], v56 src0_sel:WORD_1
	v_pk_fma_f32 v[76:77], v[252:253], v[132:133], v[76:77] op_sel_hi:[0,1,1]
	v_lshlrev_b32_e32 v142, 16, v142
	v_cvt_pk_f32_fp8_sdwa v[98:99], v52 src0_sel:WORD_1
	v_pk_fma_f32 v[76:77], v[142:143], v[226:227], v[76:77] op_sel_hi:[0,1,1]
	v_lshlrev_b32_e32 v226, 16, v143
	v_cvt_pk_f32_fp8_e32 v[176:177], v73
	v_cvt_pk_f32_fp8_sdwa v[72:73], v73 src0_sel:WORD_1
	v_cvt_pk_f32_fp8_sdwa v[124:125], v48 src0_sel:WORD_1
	v_bfe_u32 v149, v153, 16, 16
	v_pk_fma_f32 v[76:77], v[226:227], v[238:239], v[76:77] op_sel_hi:[0,1,1]
	v_lshlrev_b32_e32 v140, 16, v140
	v_cvt_pk_f32_fp8_e32 v[184:185], v57
	v_cvt_pk_f32_fp8_sdwa v[56:57], v57 src0_sel:WORD_1
	v_cvt_pk_f32_fp8_sdwa v[126:127], v44 src0_sel:WORD_1
	v_lshl_or_b32 v149, v149, 7, v167
	v_pk_fma_f32 v[238:239], v[140:141], v[104:105], v[76:77] op_sel_hi:[0,1,1]
	v_pk_fma_f32 v[76:77], v[128:129], v[78:79], 0 op_sel_hi:[0,1,0]
	v_cvt_pk_f32_fp8_e32 v[192:193], v53
	v_cvt_pk_f32_fp8_sdwa v[52:53], v53 src0_sel:WORD_1
	v_cvt_pk_f32_fp8_sdwa v[216:217], v40 src0_sel:WORD_1
	v_pk_fma_f32 v[76:77], v[148:149], v[96:97], v[76:77] op_sel_hi:[0,1,1]
	v_cvt_pk_f32_fp8_e32 v[200:201], v49
	v_cvt_pk_f32_fp8_sdwa v[48:49], v49 src0_sel:WORD_1
	v_pk_fma_f32 v[76:77], v[146:147], v[98:99], v[76:77] op_sel_hi:[0,1,1]
	v_cvt_pk_f32_fp8_e32 v[208:209], v45
	v_cvt_pk_f32_fp8_sdwa v[44:45], v45 src0_sel:WORD_1
	v_cvt_pk_f32_fp8_sdwa v[228:229], v36 src0_sel:WORD_1
	v_pk_fma_f32 v[76:77], v[250:251], v[124:125], v[76:77] op_sel_hi:[0,1,1]
	v_pk_fma_f32 v[72:73], v[128:129], v[72:73], 0 op_sel_hi:[0,1,0]
	v_cvt_pk_f32_fp8_e32 v[218:219], v41
	v_cvt_pk_f32_fp8_sdwa v[40:41], v41 src0_sel:WORD_1
	v_cvt_pk_f32_fp8_sdwa v[240:241], v32 src0_sel:WORD_1
	v_pk_fma_f32 v[124:125], v[144:145], v[126:127], v[76:77] op_sel_hi:[0,1,1]
	v_pk_fma_f32 v[56:57], v[148:149], v[56:57], v[72:73] op_sel_hi:[0,1,1]
	v_cvt_pk_f32_fp8_e32 v[178:179], v74
	v_cvt_pk_f32_fp8_e32 v[230:231], v37
	v_cvt_pk_f32_fp8_sdwa v[36:37], v37 src0_sel:WORD_1
	v_pk_fma_f32 v[124:125], v[252:253], v[216:217], v[124:125] op_sel_hi:[0,1,1]
	v_cvt_pk_f32_fp8_sdwa v[216:217], v12 src0_sel:WORD_1
	v_pk_fma_f32 v[52:53], v[146:147], v[52:53], v[56:57] op_sel_hi:[0,1,1]
	v_cvt_pk_f32_fp8_e32 v[186:187], v58
	v_bfe_u32 v78, v151, 16, 16
; DI void p5b3_load_v(uint4 (&vr)[16], const unsigned (&pk)[16], const unsigned char* V8, unsigned choff) {
; #pragma unroll
;   for (int i = 0; i < 16; ++i) vr[i] = *(const uint4*)(V8 + (size_t)(unsigned)(((pk[i] >> 16) << 7) + choff));
; }
; DI void p5b3_compute(const uint4 (&vr)[16], const unsigned (&pk)[16], float* outp, const u16* xres, int t, int slice, int rsub, int ch) {
;   float o[16];
; #pragma unroll
;   for (int i = 0; i < 16; ++i) o[i] = 0.f;
; #pragma unroll
;   for (int i = 0; i < 16; ++i) {
;     const unsigned vv[4] = {vr[i].x, vr[i].y, vr[i].z, vr[i].w};
;     const float wc = __uint_as_float(pk[i] << 16);
; #pragma unroll
;     for (int j = 0; j < 4; ++j) {
;       f32x2 lo = __builtin_amdgcn_cvt_pk_f32_fp8((int)vv[j], false);
;       f32x2 hi = __builtin_amdgcn_cvt_pk_f32_fp8((int)vv[j], true);
;       o[4 * j + 0] = fmaf(wc, lo[0], o[4 * j + 0]);
;       o[4 * j + 1] = fmaf(wc, lo[1], o[4 * j + 1]);
;       o[4 * j + 2] = fmaf(wc, hi[0], o[4 * j + 2]);
;       o[4 * j + 3] = fmaf(wc, hi[1], o[4 * j + 3]);
;     }
;   }
	v_pk_fma_f32 v[48:49], v[250:251], v[48:49], v[52:53] op_sel_hi:[0,1,1]
	v_cvt_pk_f32_fp8_e32 v[194:195], v54
	v_lshl_or_b32 v78, v78, 7, v167
	v_pk_fma_f32 v[228:229], v[142:143], v[228:229], v[124:125] op_sel_hi:[0,1,1]
	v_pk_fma_f32 v[44:45], v[144:145], v[44:45], v[48:49] op_sel_hi:[0,1,1]
	v_cvt_pk_f32_fp8_e32 v[202:203], v50
	v_cvt_pk_f32_fp8_e32 v[242:243], v33
	v_cvt_pk_f32_fp8_sdwa v[32:33], v33 src0_sel:WORD_1
	global_load_dwordx4 v[104:107], v149, s[2:3]
	global_load_dwordx4 v[96:99], v147, s[2:3]
	v_pk_fma_f32 v[40:41], v[252:253], v[40:41], v[44:45] op_sel_hi:[0,1,1]
	global_load_dwordx4 v[76:79], v78, s[2:3]
	s_nop 0
	global_load_dwordx4 v[124:127], v251, s[2:3]
	global_load_dwordx2 v[132:133], v[174:175], off
	v_pk_fma_f32 v[174:175], v[226:227], v[240:241], v[228:229] op_sel_hi:[0,1,1]
	v_cvt_pk_f32_fp8_e32 v[210:211], v46
	v_pk_fma_f32 v[174:175], v[140:141], v[216:217], v[174:175] op_sel_hi:[0,1,1]
	v_cvt_pk_f32_fp8_e32 v[216:217], v13
	v_cvt_pk_f32_fp8_sdwa v[12:13], v13 src0_sel:WORD_1
	v_pk_fma_f32 v[36:37], v[142:143], v[36:37], v[40:41] op_sel_hi:[0,1,1]
	v_pk_fma_f32 v[40:41], v[128:129], v[178:179], 0 op_sel_hi:[0,1,0]
	v_cvt_pk_f32_fp8_e32 v[220:221], v42
	v_pk_fma_f32 v[40:41], v[148:149], v[186:187], v[40:41] op_sel_hi:[0,1,1]
	v_cvt_pk_f32_fp8_e32 v[232:233], v38
	v_pk_fma_f32 v[40:41], v[146:147], v[194:195], v[40:41] op_sel_hi:[0,1,1]
	v_cvt_pk_f32_fp8_e32 v[244:245], v34
	v_pk_fma_f32 v[32:33], v[226:227], v[32:33], v[36:37] op_sel_hi:[0,1,1]
	v_pk_fma_f32 v[40:41], v[250:251], v[202:203], v[40:41] op_sel_hi:[0,1,1]
	v_cvt_pk_f32_fp8_sdwa v[180:181], v74 src0_sel:WORD_1
	v_pk_fma_f32 v[32:33], v[140:141], v[12:13], v[32:33] op_sel_hi:[0,1,1]
	v_cvt_pk_f32_fp8_e32 v[12:13], v14
	v_pk_fma_f32 v[40:41], v[144:145], v[210:211], v[40:41] op_sel_hi:[0,1,1]
	v_cvt_pk_f32_fp8_sdwa v[188:189], v58 src0_sel:WORD_1
	v_pk_fma_f32 v[40:41], v[252:253], v[220:221], v[40:41] op_sel_hi:[0,1,1]
	v_cvt_pk_f32_fp8_sdwa v[196:197], v54 src0_sel:WORD_1
	v_pk_fma_f32 v[40:41], v[142:143], v[232:233], v[40:41] op_sel_hi:[0,1,1]
	v_cvt_pk_f32_fp8_sdwa v[204:205], v50 src0_sel:WORD_1
	v_pk_fma_f32 v[40:41], v[226:227], v[244:245], v[40:41] op_sel_hi:[0,1,1]
	v_cvt_pk_f32_fp8_e32 v[182:183], v75
	v_cvt_pk_f32_fp8_sdwa v[212:213], v46 src0_sel:WORD_1
	v_pk_fma_f32 v[40:41], v[140:141], v[12:13], v[40:41] op_sel_hi:[0,1,1]
	v_pk_fma_f32 v[12:13], v[128:129], v[180:181], 0 op_sel_hi:[0,1,0]
	v_cvt_pk_f32_fp8_e32 v[190:191], v59
	v_cvt_pk_f32_fp8_sdwa v[222:223], v42 src0_sel:WORD_1
	v_pk_fma_f32 v[12:13], v[148:149], v[188:189], v[12:13] op_sel_hi:[0,1,1]
	v_cvt_pk_f32_fp8_e32 v[198:199], v55
	v_cvt_pk_f32_fp8_sdwa v[234:235], v38 src0_sel:WORD_1
	v_pk_fma_f32 v[12:13], v[146:147], v[196:197], v[12:13] op_sel_hi:[0,1,1]
	v_cvt_pk_f32_fp8_e32 v[206:207], v51
	v_cvt_pk_f32_fp8_sdwa v[246:247], v34 src0_sel:WORD_1
	v_pk_fma_f32 v[12:13], v[250:251], v[204:205], v[12:13] op_sel_hi:[0,1,1]
	v_cvt_pk_f32_fp8_e32 v[214:215], v47
	v_cvt_pk_f32_fp8_sdwa v[36:37], v14 src0_sel:WORD_1
	v_pk_fma_f32 v[12:13], v[144:145], v[212:213], v[12:13] op_sel_hi:[0,1,1]
	v_pk_fma_f32 v[44:45], v[128:129], v[182:183], 0 op_sel_hi:[0,1,0]
	v_cvt_pk_f32_fp8_e32 v[224:225], v43
	v_pk_fma_f32 v[12:13], v[252:253], v[222:223], v[12:13] op_sel_hi:[0,1,1]
	v_pk_fma_f32 v[44:45], v[148:149], v[190:191], v[44:45] op_sel_hi:[0,1,1]
	v_cvt_pk_f32_fp8_e32 v[236:237], v39
	v_pk_fma_f32 v[12:13], v[142:143], v[234:235], v[12:13] op_sel_hi:[0,1,1]
	v_pk_fma_f32 v[44:45], v[146:147], v[198:199], v[44:45] op_sel_hi:[0,1,1]
	v_cvt_pk_f32_fp8_e32 v[248:249], v35
	v_pk_fma_f32 v[12:13], v[226:227], v[246:247], v[12:13] op_sel_hi:[0,1,1]
	v_pk_fma_f32 v[44:45], v[250:251], v[206:207], v[44:45] op_sel_hi:[0,1,1]
	v_cvt_pk_f32_fp8_sdwa v[74:75], v75 src0_sel:WORD_1
	v_pk_fma_f32 v[36:37], v[140:141], v[36:37], v[12:13] op_sel_hi:[0,1,1]
	v_cvt_pk_f32_fp8_e32 v[12:13], v15
	v_pk_fma_f32 v[44:45], v[144:145], v[214:215], v[44:45] op_sel_hi:[0,1,1]
	v_cvt_pk_f32_fp8_sdwa v[58:59], v59 src0_sel:WORD_1
	v_pk_fma_f32 v[44:45], v[252:253], v[224:225], v[44:45] op_sel_hi:[0,1,1]
	v_cvt_pk_f32_fp8_sdwa v[54:55], v55 src0_sel:WORD_1
	v_pk_fma_f32 v[44:45], v[142:143], v[236:237], v[44:45] op_sel_hi:[0,1,1]
	v_cvt_pk_f32_fp8_sdwa v[50:51], v51 src0_sel:WORD_1
	v_pk_fma_f32 v[44:45], v[226:227], v[248:249], v[44:45] op_sel_hi:[0,1,1]
	v_cvt_pk_f32_fp8_sdwa v[46:47], v47 src0_sel:WORD_1
	v_pk_fma_f32 v[44:45], v[140:141], v[12:13], v[44:45] op_sel_hi:[0,1,1]
	v_pk_fma_f32 v[12:13], v[128:129], v[74:75], 0 op_sel_hi:[0,1,0]
	v_cvt_pk_f32_fp8_sdwa v[42:43], v43 src0_sel:WORD_1
	v_pk_fma_f32 v[12:13], v[148:149], v[58:59], v[12:13] op_sel_hi:[0,1,1]
	v_cvt_pk_f32_fp8_sdwa v[38:39], v39 src0_sel:WORD_1
	v_pk_fma_f32 v[12:13], v[146:147], v[54:55], v[12:13] op_sel_hi:[0,1,1]
	v_cvt_pk_f32_fp8_sdwa v[34:35], v35 src0_sel:WORD_1
	v_pk_fma_f32 v[12:13], v[250:251], v[50:51], v[12:13] op_sel_hi:[0,1,1]
	v_pk_fma_f32 v[12:13], v[144:145], v[46:47], v[12:13] op_sel_hi:[0,1,1]
	v_pk_fma_f32 v[176:177], v[128:129], v[176:177], 0 op_sel_hi:[0,1,0]
	v_pk_fma_f32 v[12:13], v[252:253], v[42:43], v[12:13] op_sel_hi:[0,1,1]
	v_pk_fma_f32 v[176:177], v[148:149], v[184:185], v[176:177] op_sel_hi:[0,1,1]
	v_cvt_pk_f32_fp8_sdwa v[14:15], v15 src0_sel:WORD_1
	v_pk_fma_f32 v[12:13], v[142:143], v[38:39], v[12:13] op_sel_hi:[0,1,1]
	v_pk_fma_f32 v[176:177], v[146:147], v[192:193], v[176:177] op_sel_hi:[0,1,1]
	v_pk_fma_f32 v[12:13], v[226:227], v[34:35], v[12:13] op_sel_hi:[0,1,1]
	s_waitcnt vmcnt(23)
; #define rowror(v, ctrl) __int_as_float(__builtin_amdgcn_update_dpp(0, __float_as_int(v), (ctrl), 0xf, 0xf, false))
; DI void p5b3_compute(const uint4 (&vr)[16], const unsigned (&pk)[16], float* outp, const u16* xres, int t, int slice, int rsub, int ch) {
;     ...
; #pragma unroll
;   for (int i = 0; i < 16; ++i) {
;     const unsigned vv[4] = {vr[i].x, vr[i].y, vr[i].z, vr[i].w};
;     const float wc = __uint_as_float(pk[i] << 16);
; #pragma unroll
;     for (int j = 0; j < 4; ++j) {
;       f32x2 lo = __builtin_amdgcn_cvt_pk_f32_fp8((int)vv[j], false);
;       f32x2 hi = __builtin_amdgcn_cvt_pk_f32_fp8((int)vv[j], true);
;       o[4 * j + 0] = fmaf(wc, lo[0], o[4 * j + 0]);
;       o[4 * j + 1] = fmaf(wc, lo[1], o[4 * j + 1]);
;       o[4 * j + 2] = fmaf(wc, hi[0], o[4 * j + 2]);
;       o[4 * j + 3] = fmaf(wc, hi[1], o[4 * j + 3]);
;     }
;   }
; #pragma unroll
;   for (int i = 0; i < 16; ++i) {
;     float v = o[i];
;     v += rowror(v, 0x128);
;     v += __shfl_xor(v, 16);
;     v += __shfl_xor(v, 32);
;     o[i] = v;
;   }
	v_cvt_pk_f32_fp8_e32 v[34:35], v4
	v_pk_fma_f32 v[176:177], v[250:251], v[200:201], v[176:177] op_sel_hi:[0,1,1]
	v_cvt_pk_f32_fp8_sdwa v[38:39], v4 src0_sel:WORD_1
	v_cvt_pk_f32_fp8_e32 v[42:43], v5
	v_cvt_pk_f32_fp8_sdwa v[46:47], v5 src0_sel:WORD_1
	s_waitcnt vmcnt(22)
	v_cvt_pk_f32_fp8_e32 v[4:5], v0
	v_pk_fma_f32 v[176:177], v[144:145], v[208:209], v[176:177] op_sel_hi:[0,1,1]
	v_cvt_pk_f32_fp8_e32 v[48:49], v6
	v_cvt_pk_f32_fp8_sdwa v[50:51], v6 src0_sel:WORD_1
	v_cvt_pk_f32_fp8_e32 v[52:53], v7
	v_cvt_pk_f32_fp8_sdwa v[54:55], v7 src0_sel:WORD_1
	v_cvt_pk_f32_fp8_sdwa v[6:7], v0 src0_sel:WORD_1
	v_cvt_pk_f32_fp8_e32 v[58:59], v1
	v_cvt_pk_f32_fp8_sdwa v[72:73], v1 src0_sel:WORD_1
	s_waitcnt vmcnt(21)
	v_cvt_pk_f32_fp8_e32 v[0:1], v24
	v_pk_fma_f32 v[176:177], v[252:253], v[218:219], v[176:177] op_sel_hi:[0,1,1]
	v_pk_fma_f32 v[12:13], v[140:141], v[14:15], v[12:13] op_sel_hi:[0,1,1]
	v_lshlrev_b32_e32 v14, 16, v141
	v_cvt_pk_f32_fp8_e32 v[146:147], v26
	v_cvt_pk_f32_fp8_sdwa v[148:149], v26 src0_sel:WORD_1
	v_cvt_pk_f32_fp8_e32 v[178:179], v27
	v_cvt_pk_f32_fp8_sdwa v[180:181], v27 src0_sel:WORD_1
	s_waitcnt vmcnt(20)
	v_cvt_pk_f32_fp8_e32 v[26:27], v16
	v_pk_fma_f32 v[176:177], v[142:143], v[230:231], v[176:177] op_sel_hi:[0,1,1]
	v_lshlrev_b32_e32 v56, 16, v138
	v_cvt_pk_f32_fp8_e32 v[186:187], v18
	v_cvt_pk_f32_fp8_sdwa v[188:189], v18 src0_sel:WORD_1
	v_cvt_pk_f32_fp8_e32 v[190:191], v19
	v_cvt_pk_f32_fp8_sdwa v[192:193], v19 src0_sel:WORD_1
	s_waitcnt vmcnt(19)
	v_cvt_pk_f32_fp8_e32 v[18:19], v28
	v_pk_fma_f32 v[34:35], v[14:15], v[34:35], v[238:239] op_sel_hi:[0,1,1]
	v_pk_fma_f32 v[176:177], v[226:227], v[242:243], v[176:177] op_sel_hi:[0,1,1]
	v_lshlrev_b32_e32 v128, 16, v139
	s_waitcnt vmcnt(18)
	v_cvt_pk_f32_fp8_e32 v[206:207], v20
	v_pk_fma_f32 v[4:5], v[56:57], v[4:5], v[34:35] op_sel_hi:[0,1,1]
	v_pk_fma_f32 v[176:177], v[140:141], v[216:217], v[176:177] op_sel_hi:[0,1,1]
	v_lshlrev_b32_e32 v136, 16, v136
	v_cvt_pk_f32_fp8_e32 v[212:213], v22
	v_cvt_pk_f32_fp8_sdwa v[214:215], v22 src0_sel:WORD_1
	v_cvt_pk_f32_fp8_e32 v[216:217], v23
	v_cvt_pk_f32_fp8_sdwa v[218:219], v23 src0_sel:WORD_1
	s_waitcnt vmcnt(17)
	v_cvt_pk_f32_fp8_e32 v[22:23], v8
	v_pk_fma_f32 v[0:1], v[128:129], v[0:1], v[4:5] op_sel_hi:[0,1,1]
	v_lshlrev_b32_e32 v194, 16, v137
	v_pk_fma_f32 v[0:1], v[136:137], v[26:27], v[0:1] op_sel_hi:[0,1,1]
	v_cvt_pk_f32_fp8_e32 v[74:75], v2
	v_cvt_pk_f32_fp8_sdwa v[140:141], v2 src0_sel:WORD_1
	v_cvt_pk_f32_fp8_e32 v[142:143], v3
	v_cvt_pk_f32_fp8_sdwa v[144:145], v3 src0_sel:WORD_1
	v_cvt_pk_f32_fp8_sdwa v[2:3], v24 src0_sel:WORD_1
	v_cvt_pk_f32_fp8_e32 v[138:139], v25
	v_cvt_pk_f32_fp8_sdwa v[24:25], v25 src0_sel:WORD_1
	v_lshlrev_b32_e32 v134, 16, v134
	v_pk_fma_f32 v[0:1], v[194:195], v[18:19], v[0:1] op_sel_hi:[0,1,1]
	v_cvt_pk_f32_fp8_sdwa v[182:183], v16 src0_sel:WORD_1
	v_cvt_pk_f32_fp8_e32 v[184:185], v17
	v_cvt_pk_f32_fp8_sdwa v[16:17], v17 src0_sel:WORD_1
	v_lshlrev_b32_e32 v220, 16, v135
	v_pk_fma_f32 v[0:1], v[134:135], v[206:207], v[0:1] op_sel_hi:[0,1,1]
	v_cvt_pk_f32_fp8_sdwa v[196:197], v28 src0_sel:WORD_1
	v_cvt_pk_f32_fp8_e32 v[198:199], v29
	v_cvt_pk_f32_fp8_sdwa v[28:29], v29 src0_sel:WORD_1
	v_cvt_pk_f32_fp8_e32 v[226:227], v10
	v_cvt_pk_f32_fp8_sdwa v[228:229], v10 src0_sel:WORD_1
	v_cvt_pk_f32_fp8_e32 v[230:231], v11
	v_pk_fma_f32 v[0:1], v[220:221], v[22:23], v[0:1] op_sel_hi:[0,1,1]
	v_cvt_pk_f32_fp8_sdwa v[34:35], v11 src0_sel:WORD_1
	v_pk_fma_f32 v[10:11], v[14:15], v[42:43], v[176:177] op_sel_hi:[0,1,1]
	v_pk_fma_f32 v[22:23], v[14:15], v[46:47], v[32:33] op_sel_hi:[0,1,1]
	v_cvt_pk_f32_fp8_sdwa v[208:209], v20 src0_sel:WORD_1
	v_cvt_pk_f32_fp8_e32 v[210:211], v21
	v_cvt_pk_f32_fp8_sdwa v[20:21], v21 src0_sel:WORD_1
	v_pk_fma_f32 v[10:11], v[56:57], v[58:59], v[10:11] op_sel_hi:[0,1,1]
	v_pk_fma_f32 v[22:23], v[56:57], v[72:73], v[22:23] op_sel_hi:[0,1,1]
	v_cvt_pk_f32_fp8_sdwa v[222:223], v8 src0_sel:WORD_1
	v_cvt_pk_f32_fp8_e32 v[224:225], v9
	v_cvt_pk_f32_fp8_sdwa v[8:9], v9 src0_sel:WORD_1
	v_pk_fma_f32 v[10:11], v[128:129], v[138:139], v[10:11] op_sel_hi:[0,1,1]
	v_pk_fma_f32 v[22:23], v[128:129], v[24:25], v[22:23] op_sel_hi:[0,1,1]
	v_pk_fma_f32 v[10:11], v[136:137], v[184:185], v[10:11] op_sel_hi:[0,1,1]
	v_pk_fma_f32 v[16:17], v[136:137], v[16:17], v[22:23] op_sel_hi:[0,1,1]
	v_pk_fma_f32 v[10:11], v[194:195], v[198:199], v[10:11] op_sel_hi:[0,1,1]
	v_pk_fma_f32 v[16:17], v[194:195], v[28:29], v[16:17] op_sel_hi:[0,1,1]
	v_pk_fma_f32 v[18:19], v[14:15], v[38:39], v[174:175] op_sel_hi:[0,1,1]
	v_pk_fma_f32 v[10:11], v[134:135], v[210:211], v[10:11] op_sel_hi:[0,1,1]
	v_pk_fma_f32 v[16:17], v[134:135], v[20:21], v[16:17] op_sel_hi:[0,1,1]
	v_pk_fma_f32 v[6:7], v[56:57], v[6:7], v[18:19] op_sel_hi:[0,1,1]
	v_pk_fma_f32 v[10:11], v[220:221], v[224:225], v[10:11] op_sel_hi:[0,1,1]
	v_mov_b32_e32 v18, v129
	v_mov_b32_e32 v19, v129
	v_pk_fma_f32 v[8:9], v[220:221], v[8:9], v[16:17] op_sel_hi:[0,1,1]
	v_mov_b32_e32 v16, v129
	v_mov_b32_e32 v17, v129
	v_mov_b32_dpp v18, v10 row_ror:8 row_mask:0xf bank_mask:0xf
	v_mov_b32_dpp v19, v11 row_ror:8 row_mask:0xf bank_mask:0xf
	v_mov_b32_dpp v16, v8 row_ror:8 row_mask:0xf bank_mask:0xf
	v_mov_b32_dpp v17, v9 row_ror:8 row_mask:0xf bank_mask:0xf
	v_pk_add_f32 v[10:11], v[10:11], v[18:19]
	v_pk_add_f32 v[20:21], v[8:9], v[16:17]
	ds_bpermute_b32 v18, v170, v10
	ds_bpermute_b32 v19, v170, v11
	ds_bpermute_b32 v22, v170, v20
	ds_bpermute_b32 v23, v170, v21
	v_cvt_pk_f32_fp8_e32 v[200:201], v30
	v_cvt_pk_f32_fp8_sdwa v[202:203], v30 src0_sel:WORD_1
	s_waitcnt lgkmcnt(2)
	v_pk_add_f32 v[8:9], v[10:11], v[18:19]
	v_pk_fma_f32 v[24:25], v[14:15], v[50:51], v[36:37] op_sel_hi:[0,1,1]
	s_waitcnt lgkmcnt(0)
; #define rowror(v, ctrl) __int_as_float(__builtin_amdgcn_update_dpp(0, __float_as_int(v), (ctrl), 0xf, 0xf, false))
; DI void p5b3_compute(const uint4 (&vr)[16], const unsigned (&pk)[16], float* outp, const u16* xres, int t, int slice, int rsub, int ch) {
;     ...
; #pragma unroll
;   for (int i = 0; i < 16; ++i) {
;     float v = o[i];
;     v += rowror(v, 0x128);
;     v += __shfl_xor(v, 16);
;     v += __shfl_xor(v, 32);
;     o[i] = v;
;   }
;   if (rsub == 0) {
;     const unsigned ooff = (unsigned)t * DM + slice * 128 + ch * 16;
;     const uint4 xa = *(const uint4*)(xres + (size_t)ooff), xb4 = *(const uint4*)(xres + (size_t)(ooff + 8));
;     const unsigned xu[8] = {xa.x, xa.y, xa.z, xa.w, xb4.x, xb4.y, xb4.z, xb4.w};
; #pragma unroll
;     for (int i = 0; i < 4; ++i) {
;       const float x0 = __uint_as_float(xu[2 * i] << 16), x1 = __uint_as_float(xu[2 * i] & 0xffff0000u);
;       const float x2 = __uint_as_float(xu[2 * i + 1] << 16), x3 = __uint_as_float(xu[2 * i + 1] & 0xffff0000u);
;       *(float4*)(outp + (size_t)(ooff + 4 * i)) = make_float4(x0 + o[4 * i], x1 + o[4 * i + 1], x2 + o[4 * i + 2], x3 + o[4 * i + 3]);
;     }
;   }
	v_pk_add_f32 v[10:11], v[20:21], v[22:23]
	v_pk_fma_f32 v[20:21], v[14:15], v[48:49], v[40:41] op_sel_hi:[0,1,1]
	v_pk_fma_f32 v[20:21], v[56:57], v[74:75], v[20:21] op_sel_hi:[0,1,1]
	v_pk_fma_f32 v[24:25], v[56:57], v[140:141], v[24:25] op_sel_hi:[0,1,1]
	v_pk_fma_f32 v[20:21], v[128:129], v[146:147], v[20:21] op_sel_hi:[0,1,1]
	v_pk_fma_f32 v[24:25], v[128:129], v[148:149], v[24:25] op_sel_hi:[0,1,1]
	v_pk_fma_f32 v[20:21], v[136:137], v[186:187], v[20:21] op_sel_hi:[0,1,1]
	v_pk_fma_f32 v[24:25], v[136:137], v[188:189], v[24:25] op_sel_hi:[0,1,1]
	v_pk_fma_f32 v[20:21], v[194:195], v[200:201], v[20:21] op_sel_hi:[0,1,1]
	v_pk_fma_f32 v[24:25], v[194:195], v[202:203], v[24:25] op_sel_hi:[0,1,1]
	v_pk_fma_f32 v[20:21], v[134:135], v[212:213], v[20:21] op_sel_hi:[0,1,1]
	v_pk_fma_f32 v[24:25], v[134:135], v[214:215], v[24:25] op_sel_hi:[0,1,1]
	v_pk_fma_f32 v[20:21], v[220:221], v[226:227], v[20:21] op_sel_hi:[0,1,1]
	v_mov_b32_e32 v22, v129
	v_mov_b32_e32 v23, v129
	v_pk_fma_f32 v[24:25], v[220:221], v[228:229], v[24:25] op_sel_hi:[0,1,1]
	v_mov_b32_e32 v26, v129
	v_mov_b32_e32 v27, v129
	v_mov_b32_dpp v22, v20 row_ror:8 row_mask:0xf bank_mask:0xf
	v_mov_b32_dpp v23, v21 row_ror:8 row_mask:0xf bank_mask:0xf
	v_mov_b32_dpp v26, v24 row_ror:8 row_mask:0xf bank_mask:0xf
	v_mov_b32_dpp v27, v25 row_ror:8 row_mask:0xf bank_mask:0xf
	v_pk_add_f32 v[20:21], v[20:21], v[22:23]
	v_pk_add_f32 v[26:27], v[24:25], v[26:27]
	ds_bpermute_b32 v22, v170, v20
	ds_bpermute_b32 v23, v170, v21
	ds_bpermute_b32 v28, v170, v26
	ds_bpermute_b32 v29, v170, v27
	v_cvt_pk_f32_fp8_e32 v[204:205], v31
	v_cvt_pk_f32_fp8_sdwa v[30:31], v31 src0_sel:WORD_1
	s_waitcnt lgkmcnt(2)
	v_pk_add_f32 v[20:21], v[20:21], v[22:23]
	v_pk_fma_f32 v[12:13], v[14:15], v[54:55], v[12:13] op_sel_hi:[0,1,1]
	s_waitcnt lgkmcnt(0)
	v_pk_add_f32 v[22:23], v[26:27], v[28:29]
	v_pk_fma_f32 v[28:29], v[14:15], v[52:53], v[44:45] op_sel_hi:[0,1,1]
	v_pk_fma_f32 v[28:29], v[56:57], v[142:143], v[28:29] op_sel_hi:[0,1,1]
	v_pk_fma_f32 v[12:13], v[56:57], v[144:145], v[12:13] op_sel_hi:[0,1,1]
	v_pk_fma_f32 v[2:3], v[128:129], v[2:3], v[6:7] op_sel_hi:[0,1,1]
	v_pk_fma_f32 v[28:29], v[128:129], v[178:179], v[28:29] op_sel_hi:[0,1,1]
	v_pk_fma_f32 v[12:13], v[128:129], v[180:181], v[12:13] op_sel_hi:[0,1,1]
	v_pk_fma_f32 v[2:3], v[136:137], v[182:183], v[2:3] op_sel_hi:[0,1,1]
	v_pk_fma_f32 v[28:29], v[136:137], v[190:191], v[28:29] op_sel_hi:[0,1,1]
	v_pk_fma_f32 v[12:13], v[136:137], v[192:193], v[12:13] op_sel_hi:[0,1,1]
	v_pk_fma_f32 v[2:3], v[194:195], v[196:197], v[2:3] op_sel_hi:[0,1,1]
	v_pk_fma_f32 v[28:29], v[194:195], v[204:205], v[28:29] op_sel_hi:[0,1,1]
	v_pk_fma_f32 v[12:13], v[194:195], v[30:31], v[12:13] op_sel_hi:[0,1,1]
	v_pk_fma_f32 v[2:3], v[134:135], v[208:209], v[2:3] op_sel_hi:[0,1,1]
	v_pk_fma_f32 v[28:29], v[134:135], v[216:217], v[28:29] op_sel_hi:[0,1,1]
	v_pk_fma_f32 v[12:13], v[134:135], v[218:219], v[12:13] op_sel_hi:[0,1,1]
	v_mov_b32_e32 v4, v129
	v_mov_b32_e32 v5, v129
	v_pk_fma_f32 v[2:3], v[220:221], v[222:223], v[2:3] op_sel_hi:[0,1,1]
	v_mov_b32_e32 v6, v129
	v_mov_b32_e32 v7, v129
	v_pk_fma_f32 v[28:29], v[220:221], v[230:231], v[28:29] op_sel_hi:[0,1,1]
	v_mov_b32_e32 v32, v129
	v_mov_b32_e32 v33, v129
	v_pk_fma_f32 v[12:13], v[220:221], v[34:35], v[12:13] op_sel_hi:[0,1,1]
	v_mov_b32_e32 v14, v129
	v_mov_b32_e32 v15, v129
	v_mov_b32_dpp v4, v0 row_ror:8 row_mask:0xf bank_mask:0xf
	v_mov_b32_dpp v5, v1 row_ror:8 row_mask:0xf bank_mask:0xf
	v_mov_b32_dpp v6, v2 row_ror:8 row_mask:0xf bank_mask:0xf
	v_mov_b32_dpp v7, v3 row_ror:8 row_mask:0xf bank_mask:0xf
	v_mov_b32_dpp v32, v28 row_ror:8 row_mask:0xf bank_mask:0xf
	v_mov_b32_dpp v33, v29 row_ror:8 row_mask:0xf bank_mask:0xf
	v_mov_b32_dpp v14, v12 row_ror:8 row_mask:0xf bank_mask:0xf
	v_mov_b32_dpp v15, v13 row_ror:8 row_mask:0xf bank_mask:0xf
	v_pk_add_f32 v[0:1], v[0:1], v[4:5]
	v_pk_add_f32 v[2:3], v[2:3], v[6:7]
	v_pk_add_f32 v[28:29], v[28:29], v[32:33]
	v_pk_add_f32 v[14:15], v[12:13], v[14:15]
	ds_bpermute_b32 v4, v170, v0
	ds_bpermute_b32 v5, v170, v1
	ds_bpermute_b32 v6, v170, v2
	ds_bpermute_b32 v7, v170, v3
	ds_bpermute_b32 v32, v170, v28
	ds_bpermute_b32 v33, v170, v29
	ds_bpermute_b32 v30, v170, v14
	ds_bpermute_b32 v31, v170, v15
	s_waitcnt lgkmcnt(6)
	v_pk_add_f32 v[0:1], v[0:1], v[4:5]
	s_waitcnt lgkmcnt(4)
	v_pk_add_f32 v[2:3], v[2:3], v[6:7]
	s_waitcnt lgkmcnt(2)
	v_pk_add_f32 v[12:13], v[28:29], v[32:33]
	ds_bpermute_b32 v4, v171, v0
	s_waitcnt lgkmcnt(1)
	v_pk_add_f32 v[14:15], v[14:15], v[30:31]
	ds_bpermute_b32 v5, v171, v1
	ds_bpermute_b32 v6, v171, v2
	ds_bpermute_b32 v7, v171, v3
	ds_bpermute_b32 v16, v171, v8
	ds_bpermute_b32 v17, v171, v9
	ds_bpermute_b32 v18, v171, v10
	ds_bpermute_b32 v19, v171, v11
	ds_bpermute_b32 v24, v171, v20
	ds_bpermute_b32 v25, v171, v21
	ds_bpermute_b32 v26, v171, v22
	ds_bpermute_b32 v27, v171, v23
	ds_bpermute_b32 v28, v171, v12
	ds_bpermute_b32 v29, v171, v13
	ds_bpermute_b32 v30, v171, v14
	ds_bpermute_b32 v31, v171, v15
	s_and_saveexec_b64 s[10:11], s[0:1]
	s_cbranch_execz .LBB0_427
	v_add_u32_e32 v128, v167, v173
	v_lshl_add_u64 v[36:37], v[128:129], 1, s[6:7]
	global_load_dwordx4 v[32:35], v[36:37], off
	s_nop 0
	global_load_dwordx4 v[36:39], v[36:37], off offset:16
	s_waitcnt lgkmcnt(14)
	v_pk_add_f32 v[0:1], v[0:1], v[4:5]
	s_waitcnt lgkmcnt(12)
	v_pk_add_f32 v[2:3], v[2:3], v[6:7]
	s_waitcnt lgkmcnt(10)
	v_pk_add_f32 v[4:5], v[8:9], v[16:17]
	s_waitcnt lgkmcnt(8)
	v_pk_add_f32 v[6:7], v[10:11], v[18:19]
	s_waitcnt lgkmcnt(6)
	v_pk_add_f32 v[8:9], v[20:21], v[24:25]
	s_waitcnt lgkmcnt(4)
	v_pk_add_f32 v[10:11], v[22:23], v[26:27]
	s_waitcnt lgkmcnt(2)
	v_pk_add_f32 v[12:13], v[12:13], v[28:29]
	s_waitcnt lgkmcnt(0)
	v_pk_add_f32 v[14:15], v[14:15], v[30:31]
	v_lshl_add_u64 v[16:17], v[128:129], 2, s[4:5]
	s_waitcnt vmcnt(1)
	v_lshlrev_b32_e32 v18, 16, v32
	v_and_b32_e32 v19, 0xffff0000, v32
	v_lshlrev_b32_e32 v20, 16, v33
	v_and_b32_e32 v21, 0xffff0000, v33
	v_lshlrev_b32_e32 v22, 16, v34
	v_and_b32_e32 v23, 0xffff0000, v34
	v_lshlrev_b32_e32 v24, 16, v35
	v_and_b32_e32 v25, 0xffff0000, v35
	s_waitcnt vmcnt(0)
	v_lshlrev_b32_e32 v26, 16, v36
	v_and_b32_e32 v27, 0xffff0000, v36
	v_lshlrev_b32_e32 v28, 16, v37
	v_and_b32_e32 v29, 0xffff0000, v37
	v_lshlrev_b32_e32 v30, 16, v38
	v_and_b32_e32 v31, 0xffff0000, v38
	v_lshlrev_b32_e32 v32, 16, v39
	v_and_b32_e32 v33, 0xffff0000, v39
	v_pk_add_f32 v[0:1], v[0:1], v[18:19]
	v_pk_add_f32 v[2:3], v[2:3], v[20:21]
	v_pk_add_f32 v[4:5], v[4:5], v[22:23]
	v_pk_add_f32 v[6:7], v[6:7], v[24:25]
	v_pk_add_f32 v[8:9], v[8:9], v[26:27]
	v_pk_add_f32 v[10:11], v[10:11], v[28:29]
	v_pk_add_f32 v[12:13], v[12:13], v[30:31]
	v_pk_add_f32 v[14:15], v[14:15], v[32:33]
	global_store_dwordx4 v[16:17], v[0:3], off
	global_store_dwordx4 v[16:17], v[4:7], off offset:16
	global_store_dwordx4 v[16:17], v[8:11], off offset:32
	global_store_dwordx4 v[16:17], v[12:15], off offset:48
